# v56 + packed f32 ops split into scalar pairs in P1/P3/P7 epilogues
# speedup vs baseline: 1.0008x; 1.0008x over previous
; template <int NP> __device__ __forceinline__ void load_rs(const float* ssp, int row0, int fq, float (&rs)[2][4]) {
;     if (NP == 1) {
; #pragma unroll
;         for (int ai = 0; ai < 2; ++ai)
; #pragma unroll
;             for (int m = 0; m < 4; ++m) rs[ai][m] = ssp[row0 + ai * HALF + m * 16];
;     } else {
;         f32x4 p[2][4];
; #pragma unroll
;         for (int ai = 0; ai < 2; ++ai)
; #pragma unroll
;             for (int m = 0; m < 4; ++m) p[ai][m] = *(const f32x4*)(ssp + (size_t)(row0 + ai * HALF + m * 16) * 16 + 4 * fq);
; #pragma unroll
;         for (int ai = 0; ai < 2; ++ai)
; #pragma unroll
;             for (int m = 0; m < 4; ++m) { float s = (p[ai][m][0] + p[ai][m][1]) + (p[ai][m][2] + p[ai][m][3]); s += __shfl_xor(s, 16); s += __shfl_xor(s, 32); rs[ai][m] = s; }
;     }
; #pragma unroll
;     for (int ai = 0; ai < 2; ++ai)
; #pragma unroll
;     __device__ __forceinline__ void operator()(const f32x4 (&acc)[2][2][4][2], const Unit& u, int wr, int wc, int fr, int fq) const {
;         const int row0 = u.pm * BM + wr * 64 + fr, col0 = u.pn * HALF + wc * 32 + 8 * fq;
;         float rs[2][4]; load_rs<NP>(ssp, row0, fq, rs);
; #pragma unroll
;         for (int ai = 0; ai < 2; ++ai)
; #pragma unroll
;             for (int m = 0; m < 4; ++m) {
;                 const int row = row0 + ai * HALF + m * 16; const float r = rs[ai][m];
;                 const float nrl = r * -1.44269504089f, r2 = r * r;
;                 unsigned pk[4];
; #pragma unroll
;                 for (int q = 0; q < 4; ++q) {
;                     const f32x4 ga = acc[ai][0][m][q >> 1], ua = acc[ai][1][m][q >> 1]; const int e0 = 2 * (q & 1);
;                     const f32x2 g = (f32x2){ga[e0], ga[e0 + 1]}, up = (f32x2){ua[e0], ua[e0 + 1]};
;                     const f32x2 t = g * nrl; f32x2 ex; ex.x = __builtin_amdgcn_exp2f(t.x); ex.y = __builtin_amdgcn_exp2f(t.y);
;                     const f32x2 d = ex + 1.0f; f32x2 rc; rc.x = __builtin_amdgcn_rcpf(d.x); rc.y = __builtin_amdgcn_rcpf(d.y);
;                     const f32x2 o = (g * up) * (rc * r2);
;                     pk[q] = cvt_pk_bf16(o.x, o.y);
;                 }
;                 u32x4 w; w.x = pk[0]; w.y = pk[1]; w.z = pk[2]; w.w = pk[3];
;                 *(u32x4*)(U + (size_t)(row >> 13) * U_SLAB + (size_t)(row & (SEQ - 1)) * U_PITCH + col0) = w;
.LBB0_156:
	s_lshl_b32 s2, s33, 8
	s_add_i32 s2, s2, s48
	v_or_b32_e32 v144, s2, v146
	v_ashrrev_i32_e32 v145, 31, v144
	v_lshl_add_u64 v[154:155], v[144:145], 2, s[72:73]
	global_load_dword v145, v[154:155], off
	global_load_dword v162, v[154:155], off offset:64
	global_load_dword v163, v[154:155], off offset:128
	global_load_dword v164, v[154:155], off offset:192
	global_load_dword v165, v[154:155], off offset:512
	global_load_dword v166, v[154:155], off offset:576
	global_load_dword v167, v[154:155], off offset:640
	global_load_dword v168, v[154:155], off offset:704
	v_lshl_or_b32 v154, s57, 7, v148
	v_mul_f32_e32 v156, v108, v120
	v_mul_f32_e32 v157, v109, v121
	s_ashr_i32 s3, s2, 13
	v_mul_f32_e32 v158, v106, v114
	v_mul_f32_e32 v159, v107, v115
	v_ashrrev_i32_e32 v155, 31, v154
	v_bitop3_b32 v114, s2, v153, v146 bitop3:0xc8
	s_mul_hi_i32 s19, s3, 0x4400000
	s_mul_i32 s3, s3, 0x4400000
	v_readlane_b32 s24, v235, 44
	v_mul_f32_e32 v160, v104, v112
	v_mul_f32_e32 v161, v105, v113
	v_lshlrev_b64 v[112:113], 1, v[154:155]
	v_mul_u32_u24_e32 v114, 0xb40, v114
	v_readlane_b32 s25, v235, 45
	s_add_u32 s2, s24, s3
	v_lshlrev_b32_e32 v138, 1, v114
	s_addc_u32 s3, s25, s19
	v_lshl_add_u64 v[114:115], s[2:3], 0, v[138:139]
	v_mul_f32_e32 v124, v116, v124
	v_mul_f32_e32 v125, v117, v125
	v_mul_f32_e32 v126, v118, v126
	v_mul_f32_e32 v127, v119, v127
	v_mul_f32_e32 v122, v110, v122
	v_mul_f32_e32 v123, v111, v123
	v_lshl_add_u64 v[114:115], v[114:115], 0, v[112:113]
	v_mul_f32_e32 v96, v100, v96
	v_mul_f32_e32 v97, v101, v97
	v_mul_f32_e32 v98, v102, v98
	v_mul_f32_e32 v99, v103, v99
	v_mul_f32_e32 v88, v92, v88
	v_mul_f32_e32 v89, v93, v89
	v_mul_f32_e32 v90, v94, v90
	v_mul_f32_e32 v91, v95, v91
	v_mul_f32_e32 v80, v84, v80
	v_mul_f32_e32 v81, v85, v81
	v_mul_f32_e32 v82, v86, v82
	v_mul_f32_e32 v83, v87, v83
	v_mul_f32_e32 v72, v76, v72
	v_mul_f32_e32 v73, v77, v73
	v_mul_f32_e32 v74, v78, v74
	v_mul_f32_e32 v75, v79, v75
	v_mul_f32_e32 v64, v68, v64
	v_mul_f32_e32 v65, v69, v65
	v_mul_f32_e32 v66, v70, v66
	v_mul_f32_e32 v67, v71, v67
	s_mov_b32 s2, 0x43000
	v_mul_f32_e32 v56, v60, v56
	v_mul_f32_e32 v57, v61, v57
	v_mul_f32_e32 v58, v62, v58
	v_mul_f32_e32 v59, v63, v59
	v_mul_f32_e32 v48, v52, v48
	v_mul_f32_e32 v49, v53, v49
	v_mul_f32_e32 v50, v54, v50
	v_mul_f32_e32 v51, v55, v51
	v_mul_f32_e32 v40, v44, v40
	v_mul_f32_e32 v41, v45, v41
	v_mul_f32_e32 v42, v46, v42
	v_mul_f32_e32 v43, v47, v43
	v_mul_f32_e32 v32, v36, v32
	v_mul_f32_e32 v33, v37, v33
	v_mul_f32_e32 v34, v38, v34
	v_mul_f32_e32 v35, v39, v35
	v_mul_f32_e32 v24, v28, v24
	v_mul_f32_e32 v25, v29, v25
	v_mul_f32_e32 v26, v30, v26
	v_mul_f32_e32 v27, v31, v27
	v_mul_f32_e32 v16, v20, v16
	v_mul_f32_e32 v17, v21, v17
	v_mul_f32_e32 v18, v22, v18
	v_mul_f32_e32 v19, v23, v19
	v_mul_f32_e32 v8, v12, v8
	v_mul_f32_e32 v9, v13, v9
	v_mul_f32_e32 v10, v14, v10
	v_mul_f32_e32 v11, v15, v11
	v_mul_f32_e32 v0, v4, v0
	v_mul_f32_e32 v1, v5, v1
	v_mul_f32_e32 v2, v6, v2
	v_mul_f32_e32 v3, v7, v3
	s_waitcnt vmcnt(0)
	v_fmamk_f32 v120, v145, 0x3a800000, v152
	v_fmamk_f32 v121, v162, 0x3a800000, v152
	v_fmamk_f32 v138, v163, 0x3a800000, v152
	v_fmamk_f32 v145, v164, 0x3a800000, v152
	v_rsq_f32_e32 v164, v120
	v_fmamk_f32 v154, v165, 0x3a800000, v152
	v_rsq_f32_e32 v165, v121
	v_fmamk_f32 v162, v167, 0x3a800000, v152
	v_rsq_f32_e32 v170, v138
	v_mul_f32_e32 v138, 0xbfb8aa3b, v164
	v_fmamk_f32 v163, v168, 0x3a800000, v152
	v_rsq_f32_e32 v121, v162
	v_mul_f32_e32 v162, 0xbfb8aa3b, v165
	v_mul_f32_e32 v116, v116, v138
	v_mul_f32_e32 v117, v117, v138
	v_mul_f32_e32 v108, v108, v138
	v_mul_f32_e32 v109, v109, v138
	v_mul_f32_e32 v118, v118, v138
	v_mul_f32_e32 v119, v119, v138
	v_mul_f32_e32 v110, v110, v138
	v_mul_f32_e32 v111, v111, v138
	v_mul_f32_e32 v104, v104, v162
	v_mul_f32_e32 v105, v105, v162
	v_exp_f32_e32 v116, v116
	v_exp_f32_e32 v117, v117
	v_exp_f32_e32 v108, v108
	v_exp_f32_e32 v109, v109
	v_mul_f32_e32 v106, v106, v162
	v_mul_f32_e32 v107, v107, v162
	v_exp_f32_e32 v118, v118
	v_exp_f32_e32 v119, v119
	v_exp_f32_e32 v110, v110
	v_exp_f32_e32 v111, v111
	v_exp_f32_e32 v104, v104
	v_exp_f32_e32 v105, v105
	v_exp_f32_e32 v106, v106
	v_exp_f32_e32 v107, v107
	v_fmamk_f32 v155, v166, 0x3a800000, v152
	v_add_f32_e32 v116, 1.0, v116
	v_add_f32_e32 v117, 1.0, v117
	v_add_f32_e32 v108, 1.0, v108
	v_add_f32_e32 v109, 1.0, v109
	v_rsq_f32_e32 v155, v155
	v_add_f32_e32 v118, 1.0, v118
	v_add_f32_e32 v119, 1.0, v119
	v_add_f32_e32 v110, 1.0, v110
	v_add_f32_e32 v111, 1.0, v111
	v_add_f32_e32 v104, 1.0, v104
	v_add_f32_e32 v105, 1.0, v105
	v_rcp_f32_e32 v116, v116
	v_rcp_f32_e32 v117, v117
	v_rcp_f32_e32 v108, v108
	v_rcp_f32_e32 v109, v109
	v_add_f32_e32 v106, 1.0, v106
	v_add_f32_e32 v107, 1.0, v107
	v_rcp_f32_e32 v118, v118
	v_rcp_f32_e32 v119, v119
	v_rcp_f32_e32 v110, v110
	v_rcp_f32_e32 v111, v111
	v_rcp_f32_e32 v104, v104
	v_rcp_f32_e32 v105, v105
	v_rcp_f32_e32 v168, v106
	v_rcp_f32_e32 v169, v107
	v_rsq_f32_e32 v171, v154
	v_mul_f32_e32 v154, v164, v164
	v_mul_f32_e32 v164, v165, v165
	v_mul_f32_e32 v106, v154, v116
	v_mul_f32_e32 v107, v154, v117
	v_mul_f32_e32 v108, v154, v108
	v_mul_f32_e32 v109, v154, v109
	v_mul_f32_e32 v116, v154, v118
	v_mul_f32_e32 v117, v154, v119
	v_mul_f32_e32 v110, v154, v110
	v_mul_f32_e32 v111, v154, v111
	v_mul_f32_e32 v104, v164, v104
	v_mul_f32_e32 v105, v164, v105
	v_mul_f32_e32 v106, v124, v106
	v_mul_f32_e32 v107, v125, v107
	v_mul_f32_e32 v108, v156, v108
	v_mul_f32_e32 v109, v157, v109
	v_mul_f32_e32 v166, v100, v162
	v_mul_f32_e32 v167, v101, v162
	v_mul_f32_e32 v116, v126, v116
	v_mul_f32_e32 v117, v127, v117
	v_mul_f32_e32 v110, v122, v110
; __device__ __forceinline__ unsigned cvt_pk_bf16(float lo, float hi) { unsigned r; asm volatile("v_cvt_pk_bf16_f32 %0, %1, %2" : "=v"(r) : "v"(lo), "v"(hi)); return r; }
;     __device__ __forceinline__ void operator()(const f32x4 (&acc)[2][2][4][2], const Unit& u, int wr, int wc, int fr, int fq) const {
;     ...
;                 const int row = row0 + ai * HALF + m * 16; const float r = rs[ai][m];
;                 const float nrl = r * -1.44269504089f, r2 = r * r;
;                 unsigned pk[4];
; #pragma unroll
;                 for (int q = 0; q < 4; ++q) {
;                     const f32x4 ga = acc[ai][0][m][q >> 1], ua = acc[ai][1][m][q >> 1]; const int e0 = 2 * (q & 1);
;                     const f32x2 g = (f32x2){ga[e0], ga[e0 + 1]}, up = (f32x2){ua[e0], ua[e0 + 1]};
;                     const f32x2 t = g * nrl; f32x2 ex; ex.x = __builtin_amdgcn_exp2f(t.x); ex.y = __builtin_amdgcn_exp2f(t.y);
;                     const f32x2 d = ex + 1.0f; f32x2 rc; rc.x = __builtin_amdgcn_rcpf(d.x); rc.y = __builtin_amdgcn_rcpf(d.y);
;                     const f32x2 o = (g * up) * (rc * r2);
;                     pk[q] = cvt_pk_bf16(o.x, o.y);
;                 }
;                 u32x4 w; w.x = pk[0]; w.y = pk[1]; w.z = pk[2]; w.w = pk[3];
;                 *(u32x4*)(U + (size_t)(row >> 13) * U_SLAB + (size_t)(row & (SEQ - 1)) * U_PITCH + col0) = w;
	v_mul_f32_e32 v111, v123, v111
	v_mul_f32_e32 v118, v160, v104
	v_mul_f32_e32 v119, v161, v105
	v_cvt_pk_bf16_f32 v104, v106, v107
	v_cvt_pk_bf16_f32 v105, v116, v117
	v_cvt_pk_bf16_f32 v106, v108, v109
	v_cvt_pk_bf16_f32 v107, v110, v111
	v_mul_f32_e32 v108, v164, v168
	v_mul_f32_e32 v109, v164, v169
	global_store_dwordx4 v[114:115], v[104:107], off
	v_mul_f32_e32 v108, v158, v108
	v_mul_f32_e32 v109, v159, v109
	v_rsq_f32_e32 v145, v145
	v_exp_f32_e32 v106, v166
	v_exp_f32_e32 v107, v167
	v_cvt_pk_bf16_f32 v104, v118, v119
	v_cvt_pk_bf16_f32 v105, v108, v109
	v_mul_f32_e32 v108, v102, v162
	v_mul_f32_e32 v109, v103, v162
	v_add_f32_e32 v106, 1.0, v106
	v_add_f32_e32 v107, 1.0, v107
	v_exp_f32_e32 v108, v108
	v_exp_f32_e32 v109, v109
	v_rcp_f32_e32 v106, v106
	v_rcp_f32_e32 v107, v107
	v_rsq_f32_e32 v120, v163
	v_add_f32_e32 v100, 1.0, v108
	v_add_f32_e32 v101, 1.0, v109
	v_mul_f32_e32 v102, v164, v106
	v_mul_f32_e32 v103, v164, v107
	v_rcp_f32_e32 v100, v100
	v_rcp_f32_e32 v101, v101
	v_mul_f32_e32 v96, v96, v102
	v_mul_f32_e32 v97, v97, v103
	s_nop 0
	v_cvt_pk_bf16_f32 v106, v96, v97
	v_mul_f32_e32 v96, v164, v100
	v_mul_f32_e32 v97, v164, v101
	v_mul_f32_e32 v96, v98, v96
	v_mul_f32_e32 v97, v99, v97
	v_add_co_u32_e32 v100, vcc, s47, v114
	v_cvt_pk_bf16_f32 v107, v96, v97
	v_mul_f32_e32 v96, 0xbfb8aa3b, v170
	v_mul_f32_e32 v98, v92, v96
	v_mul_f32_e32 v99, v93, v96
	v_mul_f32_e32 v92, v94, v96
	v_mul_f32_e32 v93, v95, v96
	v_exp_f32_e32 v98, v98
	v_exp_f32_e32 v99, v99
	v_exp_f32_e32 v92, v92
	v_exp_f32_e32 v93, v93
	v_addc_co_u32_e32 v101, vcc, 0, v115, vcc
	v_add_f32_e32 v98, 1.0, v98
	v_add_f32_e32 v99, 1.0, v99
	v_add_f32_e32 v92, 1.0, v92
	v_add_f32_e32 v93, 1.0, v93
	v_rcp_f32_e32 v98, v98
	v_rcp_f32_e32 v99, v99
	v_rcp_f32_e32 v92, v92
	v_rcp_f32_e32 v93, v93
	global_store_dwordx4 v[100:101], v[104:107], off offset:2048
	v_mul_f32_e32 v100, v170, v170
	v_mul_f32_e32 v94, v100, v98
	v_mul_f32_e32 v95, v100, v99
	v_mul_f32_e32 v88, v88, v94
	v_mul_f32_e32 v89, v89, v95
	v_mul_f32_e32 v94, v84, v96
	v_mul_f32_e32 v95, v85, v96
	v_mul_f32_e32 v92, v100, v92
	v_mul_f32_e32 v93, v100, v93
	v_exp_f32_e32 v94, v94
	v_exp_f32_e32 v95, v95
	v_mul_f32_e32 v90, v90, v92
	v_mul_f32_e32 v91, v91, v93
	v_mul_f32_e32 v92, v86, v96
	v_mul_f32_e32 v93, v87, v96
	v_cvt_pk_bf16_f32 v88, v88, v89
	v_cvt_pk_bf16_f32 v89, v90, v91
	v_add_f32_e32 v90, 1.0, v94
	v_add_f32_e32 v91, 1.0, v95
	v_exp_f32_e32 v92, v92
	v_exp_f32_e32 v93, v93
	v_rcp_f32_e32 v90, v90
	v_rcp_f32_e32 v91, v91
	v_add_f32_e32 v84, 1.0, v92
	v_add_f32_e32 v85, 1.0, v93
	s_nop 0
	v_rcp_f32_e32 v84, v84
	v_rcp_f32_e32 v85, v85
	v_mul_f32_e32 v86, v100, v90
	v_mul_f32_e32 v87, v100, v91
	v_mul_f32_e32 v80, v80, v86
	v_mul_f32_e32 v81, v81, v87
	s_nop 0
	v_cvt_pk_bf16_f32 v90, v80, v81
	v_mul_f32_e32 v80, v100, v84
	v_mul_f32_e32 v81, v100, v85
	v_mul_f32_e32 v80, v82, v80
	v_mul_f32_e32 v81, v83, v81
	v_add_co_u32_e32 v84, vcc, s55, v114
	v_cvt_pk_bf16_f32 v91, v80, v81
	v_mul_f32_e32 v80, 0xbfb8aa3b, v145
	v_mul_f32_e32 v82, v76, v80
	v_mul_f32_e32 v83, v77, v80
	v_mul_f32_e32 v76, v78, v80
	v_mul_f32_e32 v77, v79, v80
	v_exp_f32_e32 v82, v82
	v_exp_f32_e32 v83, v83
	v_exp_f32_e32 v76, v76
	v_exp_f32_e32 v77, v77
	v_addc_co_u32_e32 v85, vcc, 0, v115, vcc
	v_add_f32_e32 v82, 1.0, v82
	v_add_f32_e32 v83, 1.0, v83
	v_add_f32_e32 v76, 1.0, v76
	v_add_f32_e32 v77, 1.0, v77
	v_rcp_f32_e32 v82, v82
	v_rcp_f32_e32 v83, v83
	v_rcp_f32_e32 v76, v76
	v_rcp_f32_e32 v77, v77
	global_store_dwordx4 v[84:85], v[88:91], off
	v_mul_f32_e32 v84, v145, v145
	v_mul_f32_e32 v78, v84, v82
	v_mul_f32_e32 v79, v84, v83
	v_mul_f32_e32 v72, v72, v78
	v_mul_f32_e32 v73, v73, v79
	v_mul_f32_e32 v78, v68, v80
	v_mul_f32_e32 v79, v69, v80
	v_mul_f32_e32 v76, v84, v76
	v_mul_f32_e32 v77, v84, v77
	v_exp_f32_e32 v78, v78
	v_exp_f32_e32 v79, v79
	v_mul_f32_e32 v74, v74, v76
	v_mul_f32_e32 v75, v75, v77
	v_mul_f32_e32 v76, v70, v80
	v_mul_f32_e32 v77, v71, v80
	v_cvt_pk_bf16_f32 v72, v72, v73
	v_cvt_pk_bf16_f32 v73, v74, v75
	v_add_f32_e32 v74, 1.0, v78
	v_add_f32_e32 v75, 1.0, v79
	v_exp_f32_e32 v76, v76
	v_exp_f32_e32 v77, v77
	v_rcp_f32_e32 v74, v74
	v_rcp_f32_e32 v75, v75
	v_add_f32_e32 v68, 1.0, v76
	v_add_f32_e32 v69, 1.0, v77
	s_nop 0
	v_rcp_f32_e32 v68, v68
	v_rcp_f32_e32 v69, v69
	v_mul_f32_e32 v70, v84, v74
	v_mul_f32_e32 v71, v84, v75
	v_mul_f32_e32 v64, v64, v70
	v_mul_f32_e32 v65, v65, v71
	s_nop 0
	v_cvt_pk_bf16_f32 v74, v64, v65
	v_mul_f32_e32 v64, v84, v68
	v_mul_f32_e32 v65, v84, v69
	v_mul_f32_e32 v64, v66, v64
	v_mul_f32_e32 v65, v67, v65
	v_mul_f32_e32 v68, v171, v171
	v_cvt_pk_bf16_f32 v75, v64, v65
	v_add_co_u32_e32 v64, vcc, s2, v114
	s_mov_b32 s2, 0x4400000
	s_nop 0
	v_addc_co_u32_e32 v65, vcc, 0, v115, vcc
	global_store_dwordx4 v[64:65], v[72:75], off offset:2048
	v_add_u32_e32 v65, 0x80, v144
	v_mul_f32_e32 v64, 0xbfb8aa3b, v171
	v_mul_f32_e32 v66, v60, v64
	v_mul_f32_e32 v67, v61, v64
	v_ashrrev_i32_e32 v69, 13, v65
	v_exp_f32_e32 v66, v66
	v_exp_f32_e32 v67, v67
	v_and_b32_e32 v65, 0x1fcf, v65
	v_mul_f32_e32 v60, v62, v64
	v_mul_f32_e32 v61, v63, v64
	v_add_f32_e32 v66, 1.0, v66
	v_add_f32_e32 v67, 1.0, v67
	v_exp_f32_e32 v60, v60
	v_exp_f32_e32 v61, v61
	v_rcp_f32_e32 v66, v66
	v_rcp_f32_e32 v67, v67
	v_add_f32_e32 v60, 1.0, v60
	v_add_f32_e32 v61, 1.0, v61
	s_nop 0
	v_rcp_f32_e32 v60, v60
	v_rcp_f32_e32 v61, v61
	v_mul_f32_e32 v62, v68, v66
	v_mul_f32_e32 v63, v68, v67
	v_mul_f32_e32 v56, v56, v62
	v_mul_f32_e32 v57, v57, v63
	v_mul_f32_e32 v62, v52, v64
	v_mul_f32_e32 v63, v53, v64
	v_mul_f32_e32 v60, v68, v60
	v_mul_f32_e32 v61, v68, v61
	v_exp_f32_e32 v62, v62
	v_exp_f32_e32 v63, v63
; __device__ __forceinline__ unsigned cvt_pk_bf16(float lo, float hi) { unsigned r; asm volatile("v_cvt_pk_bf16_f32 %0, %1, %2" : "=v"(r) : "v"(lo), "v"(hi)); return r; }
;     __device__ __forceinline__ void operator()(const f32x4 (&acc)[2][2][4][2], const Unit& u, int wr, int wc, int fr, int fq) const {
;     ...
;                 const int row = row0 + ai * HALF + m * 16; const float r = rs[ai][m];
;                 const float nrl = r * -1.44269504089f, r2 = r * r;
;                 unsigned pk[4];
; #pragma unroll
;                 for (int q = 0; q < 4; ++q) {
;                     const f32x4 ga = acc[ai][0][m][q >> 1], ua = acc[ai][1][m][q >> 1]; const int e0 = 2 * (q & 1);
;                     const f32x2 g = (f32x2){ga[e0], ga[e0 + 1]}, up = (f32x2){ua[e0], ua[e0 + 1]};
;                     const f32x2 t = g * nrl; f32x2 ex; ex.x = __builtin_amdgcn_exp2f(t.x); ex.y = __builtin_amdgcn_exp2f(t.y);
;                     const f32x2 d = ex + 1.0f; f32x2 rc; rc.x = __builtin_amdgcn_rcpf(d.x); rc.y = __builtin_amdgcn_rcpf(d.y);
;                     const f32x2 o = (g * up) * (rc * r2);
;                     pk[q] = cvt_pk_bf16(o.x, o.y);
;                 }
;                 u32x4 w; w.x = pk[0]; w.y = pk[1]; w.z = pk[2]; w.w = pk[3];
;                 *(u32x4*)(U + (size_t)(row >> 13) * U_SLAB + (size_t)(row & (SEQ - 1)) * U_PITCH + col0) = w;
	v_mul_f32_e32 v58, v58, v60
	v_mul_f32_e32 v59, v59, v61
	v_mul_f32_e32 v60, v54, v64
	v_mul_f32_e32 v61, v55, v64
	v_cvt_pk_bf16_f32 v56, v56, v57
	v_cvt_pk_bf16_f32 v57, v58, v59
	v_add_f32_e32 v58, 1.0, v62
	v_add_f32_e32 v59, 1.0, v63
	v_exp_f32_e32 v60, v60
	v_exp_f32_e32 v61, v61
	v_rcp_f32_e32 v58, v58
	v_rcp_f32_e32 v59, v59
	v_add_f32_e32 v52, 1.0, v60
	v_add_f32_e32 v53, 1.0, v61
	s_nop 0
	v_rcp_f32_e32 v52, v52
	v_rcp_f32_e32 v53, v53
	v_mul_f32_e32 v54, v68, v58
	v_mul_f32_e32 v55, v68, v59
	v_mul_f32_e32 v48, v48, v54
	v_mul_f32_e32 v49, v49, v55
	v_mul_f32_e32 v54, v155, v155
	v_cvt_pk_bf16_f32 v58, v48, v49
	v_mul_f32_e32 v48, v68, v52
	v_mul_f32_e32 v49, v68, v53
	v_mul_f32_e32 v48, v50, v48
	v_mul_f32_e32 v49, v51, v49
	v_mul_u32_u24_e32 v50, 0xb40, v65
	v_lshlrev_b32_e32 v138, 1, v50
	v_mul_f32_e32 v50, 0xbfb8aa3b, v155
	v_mul_f32_e32 v52, v44, v50
	v_mul_f32_e32 v53, v45, v50
	v_mul_f32_e32 v44, v46, v50
	v_mul_f32_e32 v45, v47, v50
	v_exp_f32_e32 v52, v52
	v_exp_f32_e32 v53, v53
	v_exp_f32_e32 v44, v44
	v_exp_f32_e32 v45, v45
	v_cvt_pk_bf16_f32 v59, v48, v49
	v_add_f32_e32 v52, 1.0, v52
	v_add_f32_e32 v53, 1.0, v53
	v_mov_b64_e32 v[48:49], s[24:25]
	v_rcp_f32_e32 v52, v52
	v_rcp_f32_e32 v53, v53
	v_add_f32_e32 v44, 1.0, v44
	v_add_f32_e32 v45, 1.0, v45
	v_mad_i64_i32 v[48:49], s[2:3], v69, s2, v[48:49]
	v_rcp_f32_e32 v44, v44
	v_rcp_f32_e32 v45, v45
	v_mul_f32_e32 v46, v54, v52
	v_mul_f32_e32 v47, v54, v53
	v_mul_f32_e32 v40, v40, v46
	v_mul_f32_e32 v41, v41, v47
	v_mul_f32_e32 v46, v36, v50
	v_mul_f32_e32 v47, v37, v50
	v_mul_f32_e32 v44, v54, v44
	v_mul_f32_e32 v45, v54, v45
	v_exp_f32_e32 v46, v46
	v_exp_f32_e32 v47, v47
	v_mul_f32_e32 v42, v42, v44
	v_mul_f32_e32 v43, v43, v45
	v_mul_f32_e32 v44, v38, v50
	v_mul_f32_e32 v45, v39, v50
	v_lshl_add_u64 v[48:49], v[48:49], 0, v[138:139]
	v_exp_f32_e32 v44, v44
	v_exp_f32_e32 v45, v45
	v_lshl_add_u64 v[48:49], v[48:49], 0, v[112:113]
	global_store_dwordx4 v[48:49], v[56:59], off
	v_cvt_pk_bf16_f32 v40, v40, v41
	v_cvt_pk_bf16_f32 v41, v42, v43
	v_add_f32_e32 v42, 1.0, v46
	v_add_f32_e32 v43, 1.0, v47
	v_add_f32_e32 v36, 1.0, v44
	v_add_f32_e32 v37, 1.0, v45
	v_rcp_f32_e32 v42, v42
	v_rcp_f32_e32 v43, v43
	v_rcp_f32_e32 v36, v36
	v_rcp_f32_e32 v37, v37
	v_mul_f32_e32 v38, v54, v42
	v_mul_f32_e32 v39, v54, v43
	v_mul_f32_e32 v32, v32, v38
	v_mul_f32_e32 v33, v33, v39
	s_nop 0
	v_cvt_pk_bf16_f32 v42, v32, v33
	v_mul_f32_e32 v32, v54, v36
	v_mul_f32_e32 v33, v54, v37
	v_mul_f32_e32 v32, v34, v32
	v_mul_f32_e32 v33, v35, v33
	v_add_co_u32_e32 v36, vcc, s47, v48
	v_cvt_pk_bf16_f32 v43, v32, v33
	v_mul_f32_e32 v32, 0xbfb8aa3b, v121
	v_mul_f32_e32 v34, v28, v32
	v_mul_f32_e32 v35, v29, v32
	v_mul_f32_e32 v28, v30, v32
	v_mul_f32_e32 v29, v31, v32
	v_exp_f32_e32 v34, v34
	v_exp_f32_e32 v35, v35
	v_exp_f32_e32 v28, v28
	v_exp_f32_e32 v29, v29
	v_addc_co_u32_e32 v37, vcc, 0, v49, vcc
	v_add_f32_e32 v34, 1.0, v34
	v_add_f32_e32 v35, 1.0, v35
	v_add_f32_e32 v28, 1.0, v28
	v_add_f32_e32 v29, 1.0, v29
	v_rcp_f32_e32 v34, v34
	v_rcp_f32_e32 v35, v35
	v_rcp_f32_e32 v28, v28
	v_rcp_f32_e32 v29, v29
	global_store_dwordx4 v[36:37], v[40:43], off offset:2048
	v_mul_f32_e32 v36, v121, v121
	v_mul_f32_e32 v30, v36, v34
	v_mul_f32_e32 v31, v36, v35
	v_mul_f32_e32 v24, v24, v30
	v_mul_f32_e32 v25, v25, v31
	v_mul_f32_e32 v30, v20, v32
	v_mul_f32_e32 v31, v21, v32
	v_mul_f32_e32 v28, v36, v28
	v_mul_f32_e32 v29, v36, v29
	v_exp_f32_e32 v30, v30
	v_exp_f32_e32 v31, v31
	v_mul_f32_e32 v26, v26, v28
	v_mul_f32_e32 v27, v27, v29
	v_mul_f32_e32 v28, v22, v32
	v_mul_f32_e32 v29, v23, v32
	v_cvt_pk_bf16_f32 v24, v24, v25
	v_cvt_pk_bf16_f32 v25, v26, v27
	v_add_f32_e32 v26, 1.0, v30
	v_add_f32_e32 v27, 1.0, v31
	v_exp_f32_e32 v28, v28
	v_exp_f32_e32 v29, v29
	v_rcp_f32_e32 v26, v26
	v_rcp_f32_e32 v27, v27
	v_add_f32_e32 v20, 1.0, v28
	v_add_f32_e32 v21, 1.0, v29
	s_nop 0
	v_rcp_f32_e32 v20, v20
	v_rcp_f32_e32 v21, v21
	v_mul_f32_e32 v22, v36, v26
	v_mul_f32_e32 v23, v36, v27
	v_mul_f32_e32 v16, v16, v22
	v_mul_f32_e32 v17, v17, v23
	s_nop 0
	v_cvt_pk_bf16_f32 v26, v16, v17
	v_mul_f32_e32 v16, v36, v20
	v_mul_f32_e32 v17, v36, v21
	v_mul_f32_e32 v16, v18, v16
	v_mul_f32_e32 v17, v19, v17
	v_add_co_u32_e32 v20, vcc, s55, v48
	v_cvt_pk_bf16_f32 v27, v16, v17
	v_mul_f32_e32 v16, 0xbfb8aa3b, v120
	v_mul_f32_e32 v18, v12, v16
	v_mul_f32_e32 v19, v13, v16
	v_mul_f32_e32 v12, v14, v16
	v_mul_f32_e32 v13, v15, v16
	v_exp_f32_e32 v18, v18
	v_exp_f32_e32 v19, v19
	v_exp_f32_e32 v12, v12
	v_exp_f32_e32 v13, v13
	v_addc_co_u32_e32 v21, vcc, 0, v49, vcc
	v_add_f32_e32 v18, 1.0, v18
	v_add_f32_e32 v19, 1.0, v19
	v_add_f32_e32 v12, 1.0, v12
	v_add_f32_e32 v13, 1.0, v13
	v_rcp_f32_e32 v18, v18
	v_rcp_f32_e32 v19, v19
	v_rcp_f32_e32 v12, v12
	v_rcp_f32_e32 v13, v13
	global_store_dwordx4 v[20:21], v[24:27], off
	v_mul_f32_e32 v20, v120, v120
	v_mul_f32_e32 v14, v20, v18
	v_mul_f32_e32 v15, v20, v19
	v_mul_f32_e32 v8, v8, v14
	v_mul_f32_e32 v9, v9, v15
	v_mul_f32_e32 v14, v4, v16
	v_mul_f32_e32 v15, v5, v16
	v_mul_f32_e32 v12, v20, v12
	v_mul_f32_e32 v13, v20, v13
	v_exp_f32_e32 v14, v14
	v_exp_f32_e32 v15, v15
	v_mul_f32_e32 v10, v10, v12
	v_mul_f32_e32 v11, v11, v13
	v_mul_f32_e32 v12, v6, v16
	v_mul_f32_e32 v13, v7, v16
	v_cvt_pk_bf16_f32 v8, v8, v9
	v_cvt_pk_bf16_f32 v9, v10, v11
	v_add_f32_e32 v10, 1.0, v14
	v_add_f32_e32 v11, 1.0, v15
	v_exp_f32_e32 v12, v12
	v_exp_f32_e32 v13, v13
	v_rcp_f32_e32 v10, v10
	v_rcp_f32_e32 v11, v11
	v_add_f32_e32 v4, 1.0, v12
	v_add_f32_e32 v5, 1.0, v13
	s_nop 0
	v_rcp_f32_e32 v4, v4
	v_rcp_f32_e32 v5, v5
	v_mul_f32_e32 v6, v20, v10
	v_mul_f32_e32 v7, v20, v11
	v_mul_f32_e32 v0, v0, v6
	v_mul_f32_e32 v1, v1, v7
	s_nop 0
	v_cvt_pk_bf16_f32 v10, v0, v1
	v_mul_f32_e32 v0, v20, v4
	v_mul_f32_e32 v1, v20, v5
	v_mul_f32_e32 v0, v2, v0
	v_mul_f32_e32 v1, v3, v1
	s_nop 0
	v_cvt_pk_bf16_f32 v11, v0, v1
	v_add_co_u32_e32 v0, vcc, 0x43000, v48
	s_nop 1
	v_addc_co_u32_e32 v1, vcc, 0, v49, vcc
	s_andn2_b64 vcc, exec, s[0:1]
	s_mov_b64 s[0:1], -1
	global_store_dwordx4 v[0:1], v[8:11], off offset:2048
	s_cbranch_vccnz .LBB0_149
	s_andn2_b64 vcc, exec, s[8:9]
	s_cbranch_vccnz .LBB0_148
	s_barrier
	s_branch .LBB0_148

; template <int NP> __device__ __forceinline__ void load_rs(const float* ssp, int row0, int fq, float (&rs)[2][4]) {
;     ...
;         f32x4 p[2][4];
; #pragma unroll
;         for (int ai = 0; ai < 2; ++ai)
; #pragma unroll
;             for (int m = 0; m < 4; ++m) p[ai][m] = *(const f32x4*)(ssp + (size_t)(row0 + ai * HALF + m * 16) * 16 + 4 * fq);
; #pragma unroll
;         for (int ai = 0; ai < 2; ++ai)
; #pragma unroll
;             for (int m = 0; m < 4; ++m) { float s = (p[ai][m][0] + p[ai][m][1]) + (p[ai][m][2] + p[ai][m][3]); s += __shfl_xor(s, 16); s += __shfl_xor(s, 32); rs[ai][m] = s; }
;     template <bool GATE> __device__ __forceinline__ void body(const f32x4 (&acc)[2][2][4][2], const Unit& u, int wr, int wc, int fr, int fq) const {
;         const int row0 = u.pm * BM + wr * 64 + fr, col0 = u.pn * BM + wc * 32 + 8 * fq;
;         float rs[2][4]; load_rs<16>(ssp, row0, fq, rs);
; #pragma unroll
;         for (int ai = 0; ai < 2; ++ai)
; #pragma unroll
;             for (int m = 0; m < 4; ++m) {
;                 const int row = row0 + ai * HALF + m * 16; const float r = rs[ai][m], nrl = r * -1.44269504089f;
.LBB0_382:
	v_lshl_add_u32 v186, s33, 8, v193
	v_or_b32_e32 v184, 16, v186
	v_ashrrev_i32_e32 v187, 31, v186
	v_ashrrev_i32_e32 v185, 31, v184
	v_lshlrev_b64 v[128:129], 6, v[186:187]
	v_lshlrev_b64 v[130:131], 6, v[184:185]
	v_or_b32_e32 v182, 32, v186
	v_or_b32_e32 v180, 48, v186
	v_lshl_add_u64 v[128:129], v[162:163], 0, v[128:129]
	v_lshl_add_u64 v[130:131], v[162:163], 0, v[130:131]
	v_ashrrev_i32_e32 v183, 31, v182
	v_ashrrev_i32_e32 v181, 31, v180
	global_load_dwordx4 v[148:151], v[128:129], off
	global_load_dwordx4 v[204:207], v[130:131], off
	v_lshlrev_b64 v[128:129], 6, v[182:183]
	v_lshlrev_b64 v[130:131], 6, v[180:181]
	v_add_u32_e32 v178, 0x80, v186
	v_add_u32_e32 v176, 0x90, v186
	v_lshl_add_u64 v[128:129], v[162:163], 0, v[128:129]
	v_lshl_add_u64 v[130:131], v[162:163], 0, v[130:131]
	v_ashrrev_i32_e32 v179, 31, v178
	v_ashrrev_i32_e32 v177, 31, v176
	global_load_dwordx4 v[208:211], v[128:129], off
	global_load_dwordx4 v[140:143], v[130:131], off
	v_lshlrev_b64 v[128:129], 6, v[178:179]
	v_lshlrev_b64 v[130:131], 6, v[176:177]
	v_add_u32_e32 v174, 0xa0, v186
	v_add_u32_e32 v170, 0xb0, v186
	v_lshl_add_u64 v[128:129], v[162:163], 0, v[128:129]
	v_lshl_add_u64 v[130:131], v[162:163], 0, v[130:131]
	v_ashrrev_i32_e32 v175, 31, v174
	v_ashrrev_i32_e32 v171, 31, v170
	global_load_dwordx4 v[144:147], v[128:129], off
	global_load_dwordx4 v[132:135], v[130:131], off
	v_lshlrev_b64 v[128:129], 6, v[174:175]
	v_lshlrev_b64 v[130:131], 6, v[170:171]
	v_lshl_add_u64 v[128:129], v[162:163], 0, v[128:129]
	v_lshl_add_u64 v[130:131], v[162:163], 0, v[130:131]
	global_load_dwordx4 v[136:139], v[128:129], off
	s_nop 0
	global_load_dwordx4 v[128:131], v[130:131], off
	v_and_b32_e32 v172, 64, v201
	v_xor_b32_e32 v171, 16, v201
	v_add_u32_e32 v172, 64, v172
	v_xor_b32_e32 v173, 32, v201
	v_cmp_lt_i32_e32 vcc, v171, v172
	s_cmp_lt_i32 s43, 9
	v_lshl_or_b32 v160, s43, 8, v197
	v_cndmask_b32_e32 v171, v201, v171, vcc
	v_cmp_lt_i32_e32 vcc, v173, v172
	v_lshlrev_b32_e32 v175, 2, v171
	s_waitcnt vmcnt(0)
	v_add_f32_e32 v148, v148, v149
	v_add_f32_e32 v149, v150, v151
	v_cndmask_b32_e32 v172, v201, v173, vcc
	v_add_f32_e32 v177, v148, v149
	v_add_f32_e32 v148, v204, v205
	v_add_f32_e32 v149, v206, v207
	v_lshlrev_b32_e32 v171, 2, v172
	v_add_f32_e32 v179, v148, v149
	v_add_f32_e32 v150, v208, v209
	v_add_f32_e32 v151, v210, v211
	v_add_f32_e32 v181, v150, v151
	s_cbranch_scc0 .LBB0_384
	v_mov_b32_e32 v236, v177
	v_mov_b32_e32 v237, v177
	s_nop 1
	v_permlane16_swap_b32_e32 v236, v237
	v_cndmask_b32_e64 v150, v237, v236, s[98:99]
	v_mov_b32_e32 v236, v179
	v_mov_b32_e32 v237, v179
	s_nop 1
	v_permlane16_swap_b32_e32 v236, v237
	v_cndmask_b32_e64 v151, v237, v236, s[98:99]
	v_mov_b32_e32 v148, v141
	v_mov_b32_e32 v149, v142
	v_mov_b32_e32 v236, v181
	v_mov_b32_e32 v237, v181
	s_nop 1
	v_permlane16_swap_b32_e32 v236, v237
	v_cndmask_b32_e64 v172, v237, v236, s[98:99]
	s_waitcnt lgkmcnt(2)
	v_add_f32_e32 v150, v177, v150
	v_mov_b32_e32 v236, v150
	v_mov_b32_e32 v237, v150
	s_nop 1
	v_permlane32_swap_b32_e32 v236, v237
	v_cndmask_b32_e64 v173, v237, v236, s[100:101]
	s_waitcnt lgkmcnt(2)
	v_add_f32_e32 v183, v179, v151
	v_mov_b32_e32 v151, v143
	v_mov_b32_e32 v236, v183
	v_mov_b32_e32 v237, v183
	s_nop 1
	v_permlane32_swap_b32_e32 v236, v237
	v_cndmask_b32_e64 v185, v237, v236, s[100:101]
	s_waitcnt lgkmcnt(2)
	v_add_f32_e32 v172, v181, v172
	s_waitcnt lgkmcnt(1)
	v_add_f32_e32 v173, v150, v173
	v_mov_b32_e32 v150, v140
	v_add_f32_e32 v148, v148, v150
	v_add_f32_e32 v149, v149, v151
	v_mov_b32_e32 v150, v144
	v_add_f32_e32 v188, v148, v149
	v_mov_b32_e32 v148, v145
	v_mov_b32_e32 v149, v146
	v_mov_b32_e32 v151, v147
	v_add_f32_e32 v148, v148, v150
	v_add_f32_e32 v149, v149, v151
	v_mov_b32_e32 v236, v188
	v_mov_b32_e32 v237, v188
	s_nop 1
	v_permlane16_swap_b32_e32 v236, v237
	v_cndmask_b32_e64 v190, v237, v236, s[98:99]
	v_add_f32_e32 v148, v148, v149
	v_mov_b32_e32 v236, v148
	v_mov_b32_e32 v237, v148
	s_nop 1
	v_permlane16_swap_b32_e32 v236, v237
	v_cndmask_b32_e64 v149, v237, v236, s[98:99]
	s_waitcnt lgkmcnt(2)
	v_add_f32_e32 v183, v183, v185
	v_mov_b32_e32 v150, v132
	s_waitcnt lgkmcnt(1)
	v_add_f32_e32 v185, v188, v190
	v_mov_b32_e32 v151, v135
	s_waitcnt lgkmcnt(0)
	v_add_f32_e32 v188, v148, v149
	v_mov_b32_e32 v148, v133
	v_mov_b32_e32 v149, v134
	v_add_f32_e32 v148, v148, v150
	v_add_f32_e32 v149, v149, v151
	v_mov_b32_e32 v150, v136
	v_add_f32_e32 v191, v148, v149
	v_mov_b32_e32 v148, v137
	v_mov_b32_e32 v149, v138
	v_mov_b32_e32 v151, v139
	v_add_f32_e32 v148, v148, v150
	v_add_f32_e32 v149, v149, v151
	v_mov_b32_e32 v150, v128
	v_add_f32_e32 v194, v148, v149
	v_mov_b32_e32 v148, v129
	v_mov_b32_e32 v149, v130
	v_mov_b32_e32 v151, v131
	v_add_f32_e32 v148, v148, v150
	v_add_f32_e32 v149, v149, v151
	v_mov_b32_e32 v236, v172
	v_mov_b32_e32 v237, v172
	s_nop 1
	v_permlane32_swap_b32_e32 v236, v237
	v_cndmask_b32_e64 v187, v237, v236, s[100:101]
	v_add_f32_e32 v148, v148, v149
	v_mov_b32_e32 v236, v148
	v_mov_b32_e32 v237, v148
	s_nop 1
	v_permlane16_swap_b32_e32 v236, v237
	v_cndmask_b32_e64 v149, v237, v236, s[98:99]
	v_mov_b32_e32 v236, v191
	v_mov_b32_e32 v237, v191
	s_nop 1
	v_permlane16_swap_b32_e32 v236, v237
	v_cndmask_b32_e64 v192, v237, v236, s[98:99]
	v_mov_b32_e32 v236, v194
	v_mov_b32_e32 v237, v194
	s_nop 1
	v_permlane16_swap_b32_e32 v236, v237
	v_cndmask_b32_e64 v203, v237, v236, s[98:99]
	s_waitcnt lgkmcnt(3)
	v_add_f32_e32 v172, v172, v187
	v_mov_b32_e32 v236, v185
	v_mov_b32_e32 v237, v185
	s_nop 1
	v_permlane32_swap_b32_e32 v236, v237
	v_cndmask_b32_e64 v187, v237, v236, s[100:101]
	s_waitcnt lgkmcnt(3)
; __device__ __forceinline__ unsigned cvt_pk_bf16(float lo, float hi) { unsigned r; asm volatile("v_cvt_pk_bf16_f32 %0, %1, %2" : "=v"(r) : "v"(lo), "v"(hi)); return r; }
; template <int NP> __device__ __forceinline__ void load_rs(const float* ssp, int row0, int fq, float (&rs)[2][4]) {
;     ...
;             for (int m = 0; m < 4; ++m) { float s = (p[ai][m][0] + p[ai][m][1]) + (p[ai][m][2] + p[ai][m][3]); s += __shfl_xor(s, 16); s += __shfl_xor(s, 32); rs[ai][m] = s; }
;     }
; #pragma unroll
;     for (int ai = 0; ai < 2; ++ai)
; #pragma unroll
;         for (int m = 0; m < 4; ++m) rs[ai][m] = __builtin_amdgcn_rsqf(rs[ai][m] * (1.0f / D_MODEL) + RMS_EPS);
;     template <bool GATE> __device__ __forceinline__ void body(const f32x4 (&acc)[2][2][4][2], const Unit& u, int wr, int wc, int fr, int fq) const {
;     ...
;                 const int row = row0 + ai * HALF + m * 16; const float r = rs[ai][m], nrl = r * -1.44269504089f;
; #pragma unroll
;                 for (int bj = 0; bj < 2; ++bj) {
;                     unsigned pk[4];
; #pragma unroll
;                     for (int q = 0; q < 4; ++q) {
;                         const f32x4 va = acc[ai][bj][m][q >> 1]; const int e0 = 2 * (q & 1);
;                         const f32x2 v = (f32x2){va[e0], va[e0 + 1]};
;                         f32x2 o;
;                         if (GATE) { const f32x2 t = v * nrl; f32x2 ex; ex.x = __builtin_amdgcn_exp2f(t.x); ex.y = __builtin_amdgcn_exp2f(t.y);
;                             const f32x2 d = ex + 1.0f; o.x = __builtin_amdgcn_rcpf(d.x); o.y = __builtin_amdgcn_rcpf(d.y); }
;                         else o = v * r;
;                         pk[q] = cvt_pk_bf16(o.x, o.y);
;                     }
;                     u32x4 w; w.x = pk[0]; w.y = pk[1]; w.z = pk[2]; w.w = pk[3];
;                     *(u32x4*)(P + (size_t)row * PITCH + col0 + bj * HALF) = w;
	v_add_f32_e32 v148, v148, v149
	v_mov_b32_e32 v236, v148
	v_mov_b32_e32 v237, v148
	s_nop 1
	v_permlane32_swap_b32_e32 v236, v237
	v_cndmask_b32_e64 v149, v237, v236, s[100:101]
	v_mov_b32_e32 v236, v188
	v_mov_b32_e32 v237, v188
	s_nop 1
	v_permlane32_swap_b32_e32 v236, v237
	v_cndmask_b32_e64 v190, v237, v236, s[100:101]
	s_waitcnt lgkmcnt(4)
	v_add_f32_e32 v150, v191, v192
	v_mov_b32_e32 v236, v150
	v_mov_b32_e32 v237, v150
	s_nop 1
	v_permlane32_swap_b32_e32 v236, v237
	v_cndmask_b32_e64 v151, v237, v236, s[100:101]
	s_waitcnt lgkmcnt(4)
	v_add_f32_e32 v191, v194, v203
	v_mov_b32_e32 v236, v191
	v_mov_b32_e32 v237, v191
	s_nop 1
	v_permlane32_swap_b32_e32 v236, v237
	v_cndmask_b32_e64 v192, v237, v236, s[100:101]
	s_waitcnt lgkmcnt(3)
	v_add_f32_e32 v148, v148, v149
	v_fmamk_f32 v149, v173, 0x3a800000, v202
	v_rsq_f32_e32 v208, v149
	v_fmamk_f32 v149, v183, 0x3a800000, v202
	v_add_f32_e32 v185, v185, v187
	v_rsq_f32_e32 v210, v149
	v_fmamk_f32 v149, v172, 0x3a800000, v202
	s_waitcnt lgkmcnt(2)
	v_add_f32_e32 v187, v188, v190
	v_rsq_f32_e32 v212, v149
	v_fmamk_f32 v149, v185, 0x3a800000, v202
	s_waitcnt lgkmcnt(1)
	v_add_f32_e32 v150, v150, v151
	v_rsq_f32_e32 v214, v149
	v_fmamk_f32 v149, v187, 0x3a800000, v202
	s_waitcnt lgkmcnt(0)
	v_add_f32_e32 v151, v191, v192
	v_rsq_f32_e32 v194, v149
	v_fmamk_f32 v149, v150, 0x3a800000, v202
	v_rsq_f32_e32 v192, v149
	v_fmamk_f32 v149, v151, 0x3a800000, v202
	v_fmamk_f32 v148, v148, 0x3a800000, v202
	v_rsq_f32_e32 v190, v149
	v_rsq_f32_e32 v188, v148
	v_mul_f32_e32 v148, v124, v208
	v_mul_f32_e32 v149, v125, v208
	v_readlane_b32 s2, v235, 44
	v_cvt_pk_bf16_f32 v204, v148, v149
	v_mul_f32_e32 v148, v126, v208
	v_mul_f32_e32 v149, v127, v208
	v_readlane_b32 s3, v235, 45
	v_cvt_pk_bf16_f32 v205, v148, v149
	v_mul_f32_e32 v148, v120, v208
	v_mul_f32_e32 v149, v121, v208
	v_ashrrev_i32_e32 v173, 31, v160
	v_cvt_pk_bf16_f32 v206, v148, v149
	v_mul_f32_e32 v148, v122, v208
	v_mul_f32_e32 v149, v123, v208
	v_mov_b32_e32 v172, v160
	v_cvt_pk_bf16_f32 v207, v148, v149
	v_mov_b64_e32 v[148:149], s[2:3]
	v_mad_i64_i32 v[216:217], s[2:3], v186, s41, v[148:149]
	v_lshlrev_b64 v[150:151], 1, v[172:173]
	v_lshl_add_u64 v[216:217], v[216:217], 0, v[150:151]
	global_store_dwordx4 v[216:217], v[204:207], off
	s_nop 1
	v_mul_f32_e32 v204, v116, v208
	v_mul_f32_e32 v205, v117, v208
	v_mul_f32_e32 v206, v118, v208
	v_mul_f32_e32 v207, v119, v208
	v_cvt_pk_bf16_f32 v204, v204, v205
	s_nop 0
	v_cvt_pk_bf16_f32 v205, v206, v207
	v_mul_f32_e32 v206, v112, v208
	v_mul_f32_e32 v207, v113, v208
	v_mul_f32_e32 v209, v115, v208
	v_mul_f32_e32 v208, v114, v208
	v_cvt_pk_bf16_f32 v206, v206, v207
	s_nop 0
	v_cvt_pk_bf16_f32 v207, v208, v209
	global_store_dwordx4 v[216:217], v[204:207], off offset:256
	v_mul_f32_e32 v208, v106, v210
	v_mul_f32_e32 v209, v107, v210
	s_nop 0
	v_mul_f32_e32 v204, v108, v210
	v_mul_f32_e32 v205, v109, v210
	v_mul_f32_e32 v206, v110, v210
	v_mul_f32_e32 v207, v111, v210
	v_cvt_pk_bf16_f32 v204, v204, v205
	s_nop 0
	v_cvt_pk_bf16_f32 v205, v206, v207
	v_mul_f32_e32 v206, v104, v210
	v_mul_f32_e32 v207, v105, v210
	s_nop 0
	v_cvt_pk_bf16_f32 v206, v206, v207
	v_cvt_pk_bf16_f32 v207, v208, v209
	v_mad_i64_i32 v[208:209], s[2:3], v184, s41, v[148:149]
	v_lshl_add_u64 v[208:209], v[208:209], 0, v[150:151]
	global_store_dwordx4 v[208:209], v[204:207], off
	s_nop 1
	v_mul_f32_e32 v204, v100, v210
	v_mul_f32_e32 v205, v101, v210
	v_mul_f32_e32 v206, v102, v210
	v_mul_f32_e32 v207, v103, v210
	v_cvt_pk_bf16_f32 v204, v204, v205
	s_nop 0
	v_cvt_pk_bf16_f32 v205, v206, v207
	v_mul_f32_e32 v206, v96, v210
	v_mul_f32_e32 v207, v97, v210
	v_mul_f32_e32 v211, v99, v210
	v_mul_f32_e32 v210, v98, v210
	v_cvt_pk_bf16_f32 v206, v206, v207
	s_nop 0
	v_cvt_pk_bf16_f32 v207, v210, v211
	global_store_dwordx4 v[208:209], v[204:207], off offset:256
	v_mul_f32_e32 v208, v90, v212
	v_mul_f32_e32 v209, v91, v212
	v_mul_f32_e32 v210, v82, v212
	v_mul_f32_e32 v211, v83, v212
	v_mul_f32_e32 v204, v92, v212
	v_mul_f32_e32 v205, v93, v212
	v_mul_f32_e32 v206, v94, v212
	v_mul_f32_e32 v207, v95, v212
	v_cvt_pk_bf16_f32 v204, v204, v205
	s_nop 0
	v_cvt_pk_bf16_f32 v205, v206, v207
	v_mul_f32_e32 v206, v88, v212
	v_mul_f32_e32 v207, v89, v212
	s_nop 0
	v_cvt_pk_bf16_f32 v206, v206, v207
	v_cvt_pk_bf16_f32 v207, v208, v209
	v_mad_i64_i32 v[208:209], s[2:3], v182, s41, v[148:149]
	v_lshl_add_u64 v[208:209], v[208:209], 0, v[150:151]
	global_store_dwordx4 v[208:209], v[204:207], off
	s_nop 1
	v_mul_f32_e32 v204, v84, v212
	v_mul_f32_e32 v205, v85, v212
	v_mul_f32_e32 v206, v86, v212
	v_mul_f32_e32 v207, v87, v212
	v_cvt_pk_bf16_f32 v204, v204, v205
	s_nop 0
	v_cvt_pk_bf16_f32 v205, v206, v207
	v_mul_f32_e32 v206, v80, v212
	v_mul_f32_e32 v207, v81, v212
	s_nop 0
	v_cvt_pk_bf16_f32 v206, v206, v207
	v_cvt_pk_bf16_f32 v207, v210, v211
	global_store_dwordx4 v[208:209], v[204:207], off offset:256
	v_mul_f32_e32 v208, v74, v214
	v_mul_f32_e32 v209, v75, v214
	v_mul_f32_e32 v210, v66, v214
	v_mul_f32_e32 v211, v67, v214
	v_mul_f32_e32 v204, v76, v214
	v_mul_f32_e32 v205, v77, v214
; __device__ __forceinline__ unsigned cvt_pk_bf16(float lo, float hi) { unsigned r; asm volatile("v_cvt_pk_bf16_f32 %0, %1, %2" : "=v"(r) : "v"(lo), "v"(hi)); return r; }
;     template <bool GATE> __device__ __forceinline__ void body(const f32x4 (&acc)[2][2][4][2], const Unit& u, int wr, int wc, int fr, int fq) const {
;     ...
;                 const int row = row0 + ai * HALF + m * 16; const float r = rs[ai][m], nrl = r * -1.44269504089f;
; #pragma unroll
;                 for (int bj = 0; bj < 2; ++bj) {
;                     unsigned pk[4];
; #pragma unroll
;                     for (int q = 0; q < 4; ++q) {
;                         const f32x4 va = acc[ai][bj][m][q >> 1]; const int e0 = 2 * (q & 1);
;                         const f32x2 v = (f32x2){va[e0], va[e0 + 1]};
;                         f32x2 o;
;                         if (GATE) { const f32x2 t = v * nrl; f32x2 ex; ex.x = __builtin_amdgcn_exp2f(t.x); ex.y = __builtin_amdgcn_exp2f(t.y);
;                             const f32x2 d = ex + 1.0f; o.x = __builtin_amdgcn_rcpf(d.x); o.y = __builtin_amdgcn_rcpf(d.y); }
;                         else o = v * r;
;                         pk[q] = cvt_pk_bf16(o.x, o.y);
;                     }
;                     u32x4 w; w.x = pk[0]; w.y = pk[1]; w.z = pk[2]; w.w = pk[3];
;                     *(u32x4*)(P + (size_t)row * PITCH + col0 + bj * HALF) = w;
	v_mul_f32_e32 v206, v78, v214
	v_mul_f32_e32 v207, v79, v214
	v_cvt_pk_bf16_f32 v204, v204, v205
	s_nop 0
	v_cvt_pk_bf16_f32 v205, v206, v207
	v_mul_f32_e32 v206, v72, v214
	v_mul_f32_e32 v207, v73, v214
	s_nop 0
	v_cvt_pk_bf16_f32 v206, v206, v207
	v_cvt_pk_bf16_f32 v207, v208, v209
	v_mad_i64_i32 v[208:209], s[2:3], v180, s41, v[148:149]
	v_lshl_add_u64 v[208:209], v[208:209], 0, v[150:151]
	global_store_dwordx4 v[208:209], v[204:207], off
	s_nop 1
	v_mul_f32_e32 v204, v68, v214
	v_mul_f32_e32 v205, v69, v214
	v_mul_f32_e32 v206, v70, v214
	v_mul_f32_e32 v207, v71, v214
	v_cvt_pk_bf16_f32 v204, v204, v205
	s_nop 0
	v_cvt_pk_bf16_f32 v205, v206, v207
	v_mul_f32_e32 v206, v64, v214
	v_mul_f32_e32 v207, v65, v214
	s_nop 0
	v_cvt_pk_bf16_f32 v206, v206, v207
	v_cvt_pk_bf16_f32 v207, v210, v211
	global_store_dwordx4 v[208:209], v[204:207], off offset:256
	v_mul_f32_e32 v208, v58, v194
	v_mul_f32_e32 v209, v59, v194
	v_mul_f32_e32 v210, v50, v194
	v_mul_f32_e32 v211, v51, v194
	v_mul_f32_e32 v204, v60, v194
	v_mul_f32_e32 v205, v61, v194
	v_mul_f32_e32 v206, v62, v194
	v_mul_f32_e32 v207, v63, v194
	v_cvt_pk_bf16_f32 v204, v204, v205
	s_nop 0
	v_cvt_pk_bf16_f32 v205, v206, v207
	v_mul_f32_e32 v206, v56, v194
	v_mul_f32_e32 v207, v57, v194
	s_nop 0
	v_cvt_pk_bf16_f32 v206, v206, v207
	v_cvt_pk_bf16_f32 v207, v208, v209
	v_mad_i64_i32 v[208:209], s[2:3], v178, s41, v[148:149]
	v_lshl_add_u64 v[208:209], v[208:209], 0, v[150:151]
	global_store_dwordx4 v[208:209], v[204:207], off
	s_nop 1
	v_mul_f32_e32 v204, v52, v194
	v_mul_f32_e32 v205, v53, v194
	v_mul_f32_e32 v206, v54, v194
	v_mul_f32_e32 v207, v55, v194
	v_cvt_pk_bf16_f32 v204, v204, v205
	s_nop 0
	v_cvt_pk_bf16_f32 v205, v206, v207
	v_mul_f32_e32 v206, v48, v194
	v_mul_f32_e32 v207, v49, v194
	s_nop 0
	v_cvt_pk_bf16_f32 v206, v206, v207
	v_cvt_pk_bf16_f32 v207, v210, v211
	global_store_dwordx4 v[208:209], v[204:207], off offset:256
	v_mul_f32_e32 v208, v42, v192
	v_mul_f32_e32 v209, v43, v192
	v_mul_f32_e32 v210, v34, v192
	v_mul_f32_e32 v211, v35, v192
	v_mul_f32_e32 v204, v44, v192
	v_mul_f32_e32 v205, v45, v192
	v_mul_f32_e32 v206, v46, v192
	v_mul_f32_e32 v207, v47, v192
	v_cvt_pk_bf16_f32 v204, v204, v205
	s_nop 0
	v_cvt_pk_bf16_f32 v205, v206, v207
	v_mul_f32_e32 v206, v40, v192
	v_mul_f32_e32 v207, v41, v192
	s_nop 0
	v_cvt_pk_bf16_f32 v206, v206, v207
	v_cvt_pk_bf16_f32 v207, v208, v209
	v_mad_i64_i32 v[208:209], s[2:3], v176, s41, v[148:149]
	v_lshl_add_u64 v[208:209], v[208:209], 0, v[150:151]
	global_store_dwordx4 v[208:209], v[204:207], off
	s_nop 1
	v_mul_f32_e32 v204, v36, v192
	v_mul_f32_e32 v205, v37, v192
	v_mul_f32_e32 v206, v38, v192
	v_mul_f32_e32 v207, v39, v192
	v_cvt_pk_bf16_f32 v204, v204, v205
	s_nop 0
	v_cvt_pk_bf16_f32 v205, v206, v207
	v_mul_f32_e32 v206, v32, v192
	v_mul_f32_e32 v207, v33, v192
	s_nop 0
	v_cvt_pk_bf16_f32 v206, v206, v207
	v_cvt_pk_bf16_f32 v207, v210, v211
	global_store_dwordx4 v[208:209], v[204:207], off offset:256
	v_mul_f32_e32 v208, v26, v190
	v_mul_f32_e32 v209, v27, v190
	s_nop 0
	v_mul_f32_e32 v204, v28, v190
	v_mul_f32_e32 v205, v29, v190
	v_mul_f32_e32 v206, v30, v190
	v_mul_f32_e32 v207, v31, v190
	v_cvt_pk_bf16_f32 v204, v204, v205
	s_nop 0
	v_cvt_pk_bf16_f32 v205, v206, v207
	v_mul_f32_e32 v206, v24, v190
	v_mul_f32_e32 v207, v25, v190
	s_nop 0
	v_cvt_pk_bf16_f32 v206, v206, v207
	v_cvt_pk_bf16_f32 v207, v208, v209
	v_mad_i64_i32 v[208:209], s[2:3], v174, s41, v[148:149]
	v_lshl_add_u64 v[208:209], v[208:209], 0, v[150:151]
	global_store_dwordx4 v[208:209], v[204:207], off
	v_mad_i64_i32 v[148:149], s[2:3], v170, s41, v[148:149]
	s_nop 0
	v_mul_f32_e32 v204, v20, v190
	v_mul_f32_e32 v205, v21, v190
	v_mul_f32_e32 v206, v22, v190
	v_mul_f32_e32 v207, v23, v190
	v_cvt_pk_bf16_f32 v204, v204, v205
	v_lshl_add_u64 v[148:149], v[148:149], 0, v[150:151]
	v_cvt_pk_bf16_f32 v205, v206, v207
	v_mul_f32_e32 v206, v16, v190
	v_mul_f32_e32 v207, v17, v190
	v_mul_f32_e32 v191, v19, v190
	v_mul_f32_e32 v190, v18, v190
	v_cvt_pk_bf16_f32 v206, v206, v207
	v_mul_f32_e32 v150, v6, v188
	v_mul_f32_e32 v151, v7, v188
	v_cvt_pk_bf16_f32 v207, v190, v191
	global_store_dwordx4 v[208:209], v[204:207], off offset:256
	v_mul_f32_e32 v208, v10, v188
	v_mul_f32_e32 v209, v11, v188
	v_mad_i64_i32 v[190:191], s[2:3], v170, s41, 0
	v_mul_f32_e32 v204, v12, v188
	v_mul_f32_e32 v205, v13, v188
	v_mul_f32_e32 v206, v14, v188
	v_mul_f32_e32 v207, v15, v188
	v_cvt_pk_bf16_f32 v204, v204, v205
	s_nop 0
	v_cvt_pk_bf16_f32 v205, v206, v207
	v_mul_f32_e32 v206, v8, v188
	v_mul_f32_e32 v207, v9, v188
	s_nop 0
	v_cvt_pk_bf16_f32 v206, v206, v207
	v_cvt_pk_bf16_f32 v207, v208, v209
	global_store_dwordx4 v[148:149], v[204:207], off
	v_mul_f32_e32 v148, v4, v188
	v_mul_f32_e32 v149, v5, v188
	s_nop 0
	v_cvt_pk_bf16_f32 v148, v148, v149
	v_cvt_pk_bf16_f32 v149, v150, v151
	v_mul_f32_e32 v150, v0, v188
	v_mul_f32_e32 v151, v1, v188
	v_mul_f32_e32 v204, v2, v188
	v_mul_f32_e32 v205, v3, v188
	v_cvt_pk_bf16_f32 v150, v150, v151
	s_nop 0
	v_cvt_pk_bf16_f32 v151, v204, v205
	s_cbranch_execz .LBB0_385
	s_branch .LBB0_386

; __device__ __forceinline__ unsigned cvt_pk_bf16(float lo, float hi) { unsigned r; asm volatile("v_cvt_pk_bf16_f32 %0, %1, %2" : "=v"(r) : "v"(lo), "v"(hi)); return r; }
; template <int NP> __device__ __forceinline__ void load_rs(const float* ssp, int row0, int fq, float (&rs)[2][4]) {
;     ...
;             for (int m = 0; m < 4; ++m) p[ai][m] = *(const f32x4*)(ssp + (size_t)(row0 + ai * HALF + m * 16) * 16 + 4 * fq);
; #pragma unroll
;         for (int ai = 0; ai < 2; ++ai)
; #pragma unroll
;             for (int m = 0; m < 4; ++m) { float s = (p[ai][m][0] + p[ai][m][1]) + (p[ai][m][2] + p[ai][m][3]); s += __shfl_xor(s, 16); s += __shfl_xor(s, 32); rs[ai][m] = s; }
;     }
; #pragma unroll
;     for (int ai = 0; ai < 2; ++ai)
; #pragma unroll
;         for (int m = 0; m < 4; ++m) rs[ai][m] = __builtin_amdgcn_rsqf(rs[ai][m] * (1.0f / D_MODEL) + RMS_EPS);
;     template <bool GATE> __device__ __forceinline__ void body(const f32x4 (&acc)[2][2][4][2], const Unit& u, int wr, int wc, int fr, int fq) const {
;     ...
;                         const f32x4 va = acc[ai][bj][m][q >> 1]; const int e0 = 2 * (q & 1);
;                         const f32x2 v = (f32x2){va[e0], va[e0 + 1]};
;                         f32x2 o;
;                         if (GATE) { const f32x2 t = v * nrl; f32x2 ex; ex.x = __builtin_amdgcn_exp2f(t.x); ex.y = __builtin_amdgcn_exp2f(t.y);
;                             const f32x2 d = ex + 1.0f; o.x = __builtin_amdgcn_rcpf(d.x); o.y = __builtin_amdgcn_rcpf(d.y); }
;                         else o = v * r;
;                         pk[q] = cvt_pk_bf16(o.x, o.y);
.LBB0_385:
	v_mov_b32_e32 v236, v177
	v_mov_b32_e32 v237, v177
	s_nop 1
	v_permlane16_swap_b32_e32 v236, v237
	v_cndmask_b32_e64 v150, v237, v236, s[98:99]
	v_mov_b32_e32 v148, v141
	v_mov_b32_e32 v149, v142
	v_mov_b32_e32 v236, v179
	v_mov_b32_e32 v237, v179
	s_nop 1
	v_permlane16_swap_b32_e32 v236, v237
	v_cndmask_b32_e64 v151, v237, v236, s[98:99]
	v_mov_b32_e32 v236, v181
	v_mov_b32_e32 v237, v181
	s_nop 1
	v_permlane16_swap_b32_e32 v236, v237
	v_cndmask_b32_e64 v183, v237, v236, s[98:99]
	s_waitcnt lgkmcnt(2)
	v_add_f32_e32 v141, v177, v150
	v_mov_b32_e32 v236, v141
	v_mov_b32_e32 v237, v141
	s_nop 1
	v_permlane32_swap_b32_e32 v236, v237
	v_cndmask_b32_e64 v142, v237, v236, s[100:101]
	v_readlane_b32 s2, v235, 44
	s_waitcnt lgkmcnt(2)
	v_add_f32_e32 v150, v179, v151
	v_mov_b32_e32 v236, v150
	v_mov_b32_e32 v237, v150
	s_nop 1
	v_permlane32_swap_b32_e32 v236, v237
	v_cndmask_b32_e64 v177, v237, v236, s[100:101]
	s_waitcnt lgkmcnt(2)
	v_add_f32_e32 v151, v181, v183
	s_waitcnt lgkmcnt(1)
	v_add_f32_e32 v142, v141, v142
	v_mov_b32_e32 v141, v143
	v_add_f32_e32 v140, v148, v140
	v_add_f32_e32 v141, v149, v141
	v_mov_b32_e32 v236, v151
	v_mov_b32_e32 v237, v151
	s_nop 1
	v_permlane32_swap_b32_e32 v236, v237
	v_cndmask_b32_e64 v179, v237, v236, s[100:101]
	v_add_f32_e32 v143, v140, v141
	v_mov_b32_e32 v140, v145
	v_mov_b32_e32 v141, v146
	v_mov_b32_e32 v145, v147
	v_add_f32_e32 v140, v140, v144
	v_add_f32_e32 v141, v141, v145
	v_mov_b32_e32 v236, v143
	v_mov_b32_e32 v237, v143
	s_nop 1
	v_permlane16_swap_b32_e32 v236, v237
	v_cndmask_b32_e64 v148, v237, v236, s[98:99]
	v_add_f32_e32 v140, v140, v141
	v_mov_b32_e32 v236, v140
	v_mov_b32_e32 v237, v140
	s_nop 1
	v_permlane16_swap_b32_e32 v236, v237
	v_cndmask_b32_e64 v141, v237, v236, s[98:99]
	s_waitcnt lgkmcnt(3)
	v_add_f32_e32 v144, v150, v177
	s_waitcnt lgkmcnt(2)
	v_add_f32_e32 v145, v151, v179
	s_waitcnt lgkmcnt(1)
	v_add_f32_e32 v143, v143, v148
	v_mov_b32_e32 v236, v143
	v_mov_b32_e32 v237, v143
	s_nop 1
	v_permlane32_swap_b32_e32 v236, v237
	v_cndmask_b32_e64 v146, v237, v236, s[100:101]
	s_waitcnt lgkmcnt(1)
	v_add_f32_e32 v147, v140, v141
	v_mov_b32_e32 v140, v133
	v_mov_b32_e32 v141, v134
	v_mov_b32_e32 v133, v135
	v_add_f32_e32 v132, v140, v132
	v_add_f32_e32 v133, v141, v133
	v_mov_b32_e32 v236, v147
	v_mov_b32_e32 v237, v147
	s_nop 1
	v_permlane32_swap_b32_e32 v236, v237
	v_cndmask_b32_e64 v148, v237, v236, s[100:101]
	v_add_f32_e32 v134, v132, v133
	v_mov_b32_e32 v132, v137
	v_mov_b32_e32 v133, v138
	v_mov_b32_e32 v137, v139
	v_add_f32_e32 v132, v132, v136
	v_add_f32_e32 v133, v133, v137
	v_mov_b32_e32 v236, v134
	v_mov_b32_e32 v237, v134
	s_nop 1
	v_permlane16_swap_b32_e32 v236, v237
	v_cndmask_b32_e64 v135, v237, v236, s[98:99]
	v_add_f32_e32 v136, v132, v133
	v_mov_b32_e32 v132, v129
	v_mov_b32_e32 v133, v130
	v_mov_b32_e32 v129, v131
	v_add_f32_e32 v128, v132, v128
	v_add_f32_e32 v129, v133, v129
	v_mov_b32_e32 v236, v136
	v_mov_b32_e32 v237, v136
	s_nop 1
	v_permlane16_swap_b32_e32 v236, v237
	v_cndmask_b32_e64 v137, v237, v236, s[98:99]
	v_add_f32_e32 v128, v128, v129
	v_mov_b32_e32 v236, v128
	v_mov_b32_e32 v237, v128
	s_nop 1
	v_permlane16_swap_b32_e32 v236, v237
	v_cndmask_b32_e64 v129, v237, v236, s[98:99]
	s_waitcnt lgkmcnt(2)
	v_add_f32_e32 v130, v134, v135
	v_mov_b32_e32 v236, v130
	v_mov_b32_e32 v237, v130
	s_nop 1
	v_permlane32_swap_b32_e32 v236, v237
	v_cndmask_b32_e64 v131, v237, v236, s[100:101]
	s_waitcnt lgkmcnt(2)
	v_add_f32_e32 v132, v136, v137
	v_mov_b32_e32 v236, v132
	v_mov_b32_e32 v237, v132
	s_nop 1
	v_permlane32_swap_b32_e32 v236, v237
	v_cndmask_b32_e64 v133, v237, v236, s[100:101]
	s_waitcnt lgkmcnt(2)
	v_add_f32_e32 v128, v128, v129
	v_mov_b32_e32 v236, v128
	v_mov_b32_e32 v237, v128
	s_nop 1
	v_permlane32_swap_b32_e32 v236, v237
	v_cndmask_b32_e64 v129, v237, v236, s[100:101]
	s_waitcnt lgkmcnt(2)
	v_add_f32_e32 v130, v130, v131
	v_add_f32_e32 v134, v143, v146
	s_waitcnt lgkmcnt(1)
	v_add_f32_e32 v131, v132, v133
	v_add_f32_e32 v135, v147, v148
	s_waitcnt lgkmcnt(0)
	v_add_f32_e32 v128, v128, v129
	v_fmamk_f32 v129, v142, 0x3a800000, v202
	v_rsq_f32_e32 v132, v129
	v_fmamk_f32 v129, v144, 0x3a800000, v202
	v_rsq_f32_e32 v133, v129
	v_fmamk_f32 v129, v145, 0x3a800000, v202
	v_mul_f32_e32 v132, 0xbfb8aa3b, v132
	v_rsq_f32_e32 v136, v129
	v_mul_f32_e32 v124, v124, v132
	v_mul_f32_e32 v125, v125, v132
	v_mul_f32_e32 v120, v120, v132
	v_mul_f32_e32 v121, v121, v132
	v_exp_f32_e32 v124, v124
	v_exp_f32_e32 v125, v125
	v_mul_f32_e32 v126, v126, v132
	v_mul_f32_e32 v127, v127, v132
	v_exp_f32_e32 v120, v120
	v_exp_f32_e32 v121, v121
	v_mul_f32_e32 v122, v122, v132
	v_mul_f32_e32 v123, v123, v132
	v_exp_f32_e32 v126, v126
	v_exp_f32_e32 v127, v127
	v_exp_f32_e32 v122, v122
	v_exp_f32_e32 v123, v123
	v_fmamk_f32 v129, v134, 0x3a800000, v202
	v_rsq_f32_e32 v137, v129
	v_fmamk_f32 v129, v135, 0x3a800000, v202
	v_rsq_f32_e32 v138, v129
	v_fmamk_f32 v129, v130, 0x3a800000, v202
	v_add_f32_e32 v124, 1.0, v124
	v_add_f32_e32 v125, 1.0, v125
	v_add_f32_e32 v120, 1.0, v120
	v_add_f32_e32 v121, 1.0, v121
	v_mul_f32_e32 v116, v116, v132
	v_mul_f32_e32 v117, v117, v132
	v_mul_f32_e32 v112, v112, v132
	v_mul_f32_e32 v113, v113, v132
	v_rsq_f32_e32 v130, v129
	v_fmamk_f32 v129, v131, 0x3a800000, v202
	v_rcp_f32_e32 v131, v124
	v_rcp_f32_e32 v134, v125
	v_add_f32_e32 v124, 1.0, v126
	v_add_f32_e32 v125, 1.0, v127
	v_rcp_f32_e32 v127, v120
	v_rcp_f32_e32 v135, v121
	v_add_f32_e32 v120, 1.0, v122
	v_add_f32_e32 v121, 1.0, v123
	v_exp_f32_e32 v116, v116
	v_exp_f32_e32 v117, v117
	v_mul_f32_e32 v118, v118, v132
	v_mul_f32_e32 v119, v119, v132
	v_exp_f32_e32 v112, v112
; __device__ __forceinline__ unsigned cvt_pk_bf16(float lo, float hi) { unsigned r; asm volatile("v_cvt_pk_bf16_f32 %0, %1, %2" : "=v"(r) : "v"(lo), "v"(hi)); return r; }
;     template <bool GATE> __device__ __forceinline__ void body(const f32x4 (&acc)[2][2][4][2], const Unit& u, int wr, int wc, int fr, int fq) const {
;     ...
;                 const int row = row0 + ai * HALF + m * 16; const float r = rs[ai][m], nrl = r * -1.44269504089f;
; #pragma unroll
;                 for (int bj = 0; bj < 2; ++bj) {
;                     unsigned pk[4];
; #pragma unroll
;                     for (int q = 0; q < 4; ++q) {
;                         const f32x4 va = acc[ai][bj][m][q >> 1]; const int e0 = 2 * (q & 1);
;                         const f32x2 v = (f32x2){va[e0], va[e0 + 1]};
;                         f32x2 o;
;                         if (GATE) { const f32x2 t = v * nrl; f32x2 ex; ex.x = __builtin_amdgcn_exp2f(t.x); ex.y = __builtin_amdgcn_exp2f(t.y);
;                             const f32x2 d = ex + 1.0f; o.x = __builtin_amdgcn_rcpf(d.x); o.y = __builtin_amdgcn_rcpf(d.y); }
;                         else o = v * r;
;                         pk[q] = cvt_pk_bf16(o.x, o.y);
;                     }
;                     u32x4 w; w.x = pk[0]; w.y = pk[1]; w.z = pk[2]; w.w = pk[3];
;                     *(u32x4*)(P + (size_t)row * PITCH + col0 + bj * HALF) = w;
	v_exp_f32_e32 v113, v113
	v_mul_f32_e32 v114, v114, v132
	v_mul_f32_e32 v115, v115, v132
	v_rcp_f32_e32 v126, v124
	v_rcp_f32_e32 v125, v125
	v_rcp_f32_e32 v120, v120
	v_rcp_f32_e32 v121, v121
	v_readlane_b32 s3, v235, 45
	v_exp_f32_e32 v118, v118
	v_exp_f32_e32 v119, v119
	v_exp_f32_e32 v114, v114
	v_exp_f32_e32 v115, v115
	v_cvt_pk_bf16_f32 v124, v131, v134
	v_cvt_pk_bf16_f32 v125, v126, v125
	v_cvt_pk_bf16_f32 v126, v127, v135
	v_cvt_pk_bf16_f32 v127, v120, v121
	v_mov_b64_e32 v[120:121], s[2:3]
	v_mad_i64_i32 v[134:135], s[2:3], v186, s41, v[120:121]
	v_lshlrev_b64 v[122:123], 1, v[160:161]
	v_lshl_add_u64 v[134:135], v[134:135], 0, v[122:123]
	v_add_f32_e32 v116, 1.0, v116
	v_add_f32_e32 v117, 1.0, v117
	v_add_f32_e32 v112, 1.0, v112
	v_add_f32_e32 v113, 1.0, v113
	global_store_dwordx4 v[134:135], v[124:127], off
	v_rsq_f32_e32 v129, v129
	v_fmamk_f32 v128, v128, 0x3a800000, v202
	v_rcp_f32_e32 v124, v116
	v_rcp_f32_e32 v125, v117
	v_add_f32_e32 v116, 1.0, v118
	v_add_f32_e32 v117, 1.0, v119
	v_rcp_f32_e32 v118, v112
	v_rcp_f32_e32 v119, v113
	v_add_f32_e32 v112, 1.0, v114
	v_add_f32_e32 v113, 1.0, v115
	v_rcp_f32_e32 v116, v116
	v_rcp_f32_e32 v115, v112
	v_cvt_pk_bf16_f32 v112, v124, v125
	v_rcp_f32_e32 v117, v117
	v_rcp_f32_e32 v126, v113
	v_cvt_pk_bf16_f32 v113, v116, v117
	v_cvt_pk_bf16_f32 v114, v118, v119
	v_cvt_pk_bf16_f32 v115, v115, v126
	global_store_dwordx4 v[134:135], v[112:115], off offset:256
	v_rsq_f32_e32 v128, v128
	v_mad_i64_i32 v[190:191], s[2:3], v170, s41, 0
	v_mul_f32_e32 v112, 0xbfb8aa3b, v133
	v_mul_f32_e32 v108, v108, v112
	v_mul_f32_e32 v109, v109, v112
	v_mul_f32_e32 v110, v110, v112
	v_mul_f32_e32 v111, v111, v112
	v_exp_f32_e32 v108, v108
	v_exp_f32_e32 v109, v109
	v_exp_f32_e32 v110, v110
	v_exp_f32_e32 v111, v111
	v_add_f32_e32 v108, 1.0, v108
	v_add_f32_e32 v109, 1.0, v109
	s_nop 0
	v_rcp_f32_e32 v113, v108
	v_rcp_f32_e32 v114, v109
	v_add_f32_e32 v108, 1.0, v110
	v_add_f32_e32 v109, 1.0, v111
	v_mul_f32_e32 v104, v104, v112
	v_mul_f32_e32 v105, v105, v112
	s_nop 0
	v_exp_f32_e32 v104, v104
	v_exp_f32_e32 v105, v105
	v_mul_f32_e32 v106, v106, v112
	v_mul_f32_e32 v107, v107, v112
	v_mul_f32_e32 v100, v100, v112
	v_mul_f32_e32 v101, v101, v112
	v_exp_f32_e32 v106, v106
	v_exp_f32_e32 v107, v107
	v_mul_f32_e32 v96, v96, v112
	v_mul_f32_e32 v97, v97, v112
	v_exp_f32_e32 v100, v100
	v_exp_f32_e32 v101, v101
	v_mul_f32_e32 v102, v102, v112
	v_mul_f32_e32 v103, v103, v112
	v_exp_f32_e32 v96, v96
	v_exp_f32_e32 v97, v97
	v_mul_f32_e32 v98, v98, v112
	v_mul_f32_e32 v99, v99, v112
	v_add_f32_e32 v104, 1.0, v104
	v_add_f32_e32 v105, 1.0, v105
	v_exp_f32_e32 v102, v102
	v_exp_f32_e32 v103, v103
	v_exp_f32_e32 v98, v98
	v_exp_f32_e32 v99, v99
	v_rcp_f32_e32 v108, v108
	v_rcp_f32_e32 v109, v109
	v_rcp_f32_e32 v110, v104
	v_rcp_f32_e32 v111, v105
	v_add_f32_e32 v104, 1.0, v106
	v_add_f32_e32 v105, 1.0, v107
	v_add_f32_e32 v100, 1.0, v100
	v_add_f32_e32 v101, 1.0, v101
	v_rcp_f32_e32 v107, v104
	v_rcp_f32_e32 v115, v105
	v_cvt_pk_bf16_f32 v104, v113, v114
	v_cvt_pk_bf16_f32 v105, v108, v109
	v_mad_i64_i32 v[108:109], s[2:3], v184, s41, v[120:121]
	v_lshl_add_u64 v[108:109], v[108:109], 0, v[122:123]
	v_add_f32_e32 v96, 1.0, v96
	v_add_f32_e32 v97, 1.0, v97
	v_cvt_pk_bf16_f32 v106, v110, v111
	v_cvt_pk_bf16_f32 v107, v107, v115
	global_store_dwordx4 v[108:109], v[104:107], off
	s_nop 1
	v_rcp_f32_e32 v104, v100
	v_rcp_f32_e32 v105, v101
	v_add_f32_e32 v100, 1.0, v102
	v_add_f32_e32 v101, 1.0, v103
	v_rcp_f32_e32 v102, v96
	v_rcp_f32_e32 v103, v97
	v_add_f32_e32 v96, 1.0, v98
	v_add_f32_e32 v97, 1.0, v99
	v_rcp_f32_e32 v100, v100
	v_rcp_f32_e32 v99, v96
	v_cvt_pk_bf16_f32 v96, v104, v105
	v_rcp_f32_e32 v101, v101
	v_rcp_f32_e32 v106, v97
	v_cvt_pk_bf16_f32 v97, v100, v101
	v_cvt_pk_bf16_f32 v98, v102, v103
	v_cvt_pk_bf16_f32 v99, v99, v106
	global_store_dwordx4 v[108:109], v[96:99], off offset:256
	s_nop 1
	v_mul_f32_e32 v96, 0xbfb8aa3b, v136
	v_mul_f32_e32 v92, v92, v96
	v_mul_f32_e32 v93, v93, v96
	v_mul_f32_e32 v94, v94, v96
	v_mul_f32_e32 v95, v95, v96
	v_exp_f32_e32 v92, v92
	v_exp_f32_e32 v93, v93
	v_exp_f32_e32 v94, v94
	v_exp_f32_e32 v95, v95
	v_add_f32_e32 v92, 1.0, v92
	v_add_f32_e32 v93, 1.0, v93
	s_nop 0
	v_rcp_f32_e32 v97, v92
	v_rcp_f32_e32 v98, v93
	v_add_f32_e32 v92, 1.0, v94
	v_add_f32_e32 v93, 1.0, v95
	v_mul_f32_e32 v88, v88, v96
	v_mul_f32_e32 v89, v89, v96
	s_nop 0
	v_exp_f32_e32 v88, v88
	v_exp_f32_e32 v89, v89
	v_mul_f32_e32 v90, v90, v96
	v_mul_f32_e32 v91, v91, v96
	v_mul_f32_e32 v84, v84, v96
	v_mul_f32_e32 v85, v85, v96
	v_exp_f32_e32 v90, v90
	v_exp_f32_e32 v91, v91
	v_mul_f32_e32 v80, v80, v96
	v_mul_f32_e32 v81, v81, v96
	v_exp_f32_e32 v84, v84
	v_exp_f32_e32 v85, v85
	v_mul_f32_e32 v86, v86, v96
	v_mul_f32_e32 v87, v87, v96
	v_exp_f32_e32 v80, v80
	v_exp_f32_e32 v81, v81
	v_mul_f32_e32 v82, v82, v96
	v_mul_f32_e32 v83, v83, v96
	v_add_f32_e32 v88, 1.0, v88
	v_add_f32_e32 v89, 1.0, v89
	v_exp_f32_e32 v86, v86
	v_exp_f32_e32 v87, v87
	v_exp_f32_e32 v82, v82
	v_exp_f32_e32 v83, v83
	v_rcp_f32_e32 v92, v92
	v_rcp_f32_e32 v93, v93
	v_rcp_f32_e32 v94, v88
	v_rcp_f32_e32 v95, v89
	v_add_f32_e32 v88, 1.0, v90
	v_add_f32_e32 v89, 1.0, v91
	v_add_f32_e32 v84, 1.0, v84
	v_add_f32_e32 v85, 1.0, v85
	v_rcp_f32_e32 v91, v88
	v_rcp_f32_e32 v99, v89
	v_cvt_pk_bf16_f32 v88, v97, v98
	v_cvt_pk_bf16_f32 v89, v92, v93
	v_mad_i64_i32 v[92:93], s[2:3], v182, s41, v[120:121]
	v_lshl_add_u64 v[92:93], v[92:93], 0, v[122:123]
	v_add_f32_e32 v80, 1.0, v80
	v_add_f32_e32 v81, 1.0, v81
	v_cvt_pk_bf16_f32 v90, v94, v95
	v_cvt_pk_bf16_f32 v91, v91, v99
	global_store_dwordx4 v[92:93], v[88:91], off
	s_nop 1
; __device__ __forceinline__ unsigned cvt_pk_bf16(float lo, float hi) { unsigned r; asm volatile("v_cvt_pk_bf16_f32 %0, %1, %2" : "=v"(r) : "v"(lo), "v"(hi)); return r; }
;     template <bool GATE> __device__ __forceinline__ void body(const f32x4 (&acc)[2][2][4][2], const Unit& u, int wr, int wc, int fr, int fq) const {
;     ...
;                 const int row = row0 + ai * HALF + m * 16; const float r = rs[ai][m], nrl = r * -1.44269504089f;
; #pragma unroll
;                 for (int bj = 0; bj < 2; ++bj) {
;                     unsigned pk[4];
; #pragma unroll
;                     for (int q = 0; q < 4; ++q) {
;                         const f32x4 va = acc[ai][bj][m][q >> 1]; const int e0 = 2 * (q & 1);
;                         const f32x2 v = (f32x2){va[e0], va[e0 + 1]};
;                         f32x2 o;
;                         if (GATE) { const f32x2 t = v * nrl; f32x2 ex; ex.x = __builtin_amdgcn_exp2f(t.x); ex.y = __builtin_amdgcn_exp2f(t.y);
;                             const f32x2 d = ex + 1.0f; o.x = __builtin_amdgcn_rcpf(d.x); o.y = __builtin_amdgcn_rcpf(d.y); }
;                         else o = v * r;
;                         pk[q] = cvt_pk_bf16(o.x, o.y);
;                     }
;                     u32x4 w; w.x = pk[0]; w.y = pk[1]; w.z = pk[2]; w.w = pk[3];
;                     *(u32x4*)(P + (size_t)row * PITCH + col0 + bj * HALF) = w;
	v_rcp_f32_e32 v88, v84
	v_rcp_f32_e32 v89, v85
	v_add_f32_e32 v84, 1.0, v86
	v_add_f32_e32 v85, 1.0, v87
	v_rcp_f32_e32 v86, v80
	v_rcp_f32_e32 v87, v81
	v_add_f32_e32 v80, 1.0, v82
	v_add_f32_e32 v81, 1.0, v83
	v_rcp_f32_e32 v84, v84
	v_rcp_f32_e32 v83, v80
	v_cvt_pk_bf16_f32 v80, v88, v89
	v_rcp_f32_e32 v85, v85
	v_rcp_f32_e32 v90, v81
	v_cvt_pk_bf16_f32 v81, v84, v85
	v_cvt_pk_bf16_f32 v82, v86, v87
	v_cvt_pk_bf16_f32 v83, v83, v90
	global_store_dwordx4 v[92:93], v[80:83], off offset:256
	s_nop 1
	v_mul_f32_e32 v80, 0xbfb8aa3b, v137
	v_mul_f32_e32 v76, v76, v80
	v_mul_f32_e32 v77, v77, v80
	v_mul_f32_e32 v78, v78, v80
	v_mul_f32_e32 v79, v79, v80
	v_exp_f32_e32 v76, v76
	v_exp_f32_e32 v77, v77
	v_exp_f32_e32 v78, v78
	v_exp_f32_e32 v79, v79
	v_add_f32_e32 v76, 1.0, v76
	v_add_f32_e32 v77, 1.0, v77
	s_nop 0
	v_rcp_f32_e32 v81, v76
	v_rcp_f32_e32 v82, v77
	v_add_f32_e32 v76, 1.0, v78
	v_add_f32_e32 v77, 1.0, v79
	v_mul_f32_e32 v72, v72, v80
	v_mul_f32_e32 v73, v73, v80
	s_nop 0
	v_exp_f32_e32 v72, v72
	v_exp_f32_e32 v73, v73
	v_mul_f32_e32 v74, v74, v80
	v_mul_f32_e32 v75, v75, v80
	v_mul_f32_e32 v68, v68, v80
	v_mul_f32_e32 v69, v69, v80
	v_exp_f32_e32 v74, v74
	v_exp_f32_e32 v75, v75
	v_mul_f32_e32 v64, v64, v80
	v_mul_f32_e32 v65, v65, v80
	v_exp_f32_e32 v68, v68
	v_exp_f32_e32 v69, v69
	v_mul_f32_e32 v70, v70, v80
	v_mul_f32_e32 v71, v71, v80
	v_exp_f32_e32 v64, v64
	v_exp_f32_e32 v65, v65
	v_mul_f32_e32 v66, v66, v80
	v_mul_f32_e32 v67, v67, v80
	v_add_f32_e32 v72, 1.0, v72
	v_add_f32_e32 v73, 1.0, v73
	v_exp_f32_e32 v70, v70
	v_exp_f32_e32 v71, v71
	v_exp_f32_e32 v66, v66
	v_exp_f32_e32 v67, v67
	v_rcp_f32_e32 v76, v76
	v_rcp_f32_e32 v77, v77
	v_rcp_f32_e32 v78, v72
	v_rcp_f32_e32 v79, v73
	v_add_f32_e32 v72, 1.0, v74
	v_add_f32_e32 v73, 1.0, v75
	v_add_f32_e32 v68, 1.0, v68
	v_add_f32_e32 v69, 1.0, v69
	v_rcp_f32_e32 v75, v72
	v_rcp_f32_e32 v83, v73
	v_cvt_pk_bf16_f32 v72, v81, v82
	v_cvt_pk_bf16_f32 v73, v76, v77
	v_mad_i64_i32 v[76:77], s[2:3], v180, s41, v[120:121]
	v_lshl_add_u64 v[76:77], v[76:77], 0, v[122:123]
	v_add_f32_e32 v64, 1.0, v64
	v_add_f32_e32 v65, 1.0, v65
	v_cvt_pk_bf16_f32 v74, v78, v79
	v_cvt_pk_bf16_f32 v75, v75, v83
	global_store_dwordx4 v[76:77], v[72:75], off
	s_nop 1
	v_rcp_f32_e32 v72, v68
	v_rcp_f32_e32 v73, v69
	v_add_f32_e32 v68, 1.0, v70
	v_add_f32_e32 v69, 1.0, v71
	v_rcp_f32_e32 v70, v64
	v_rcp_f32_e32 v71, v65
	v_add_f32_e32 v64, 1.0, v66
	v_add_f32_e32 v65, 1.0, v67
	v_rcp_f32_e32 v68, v68
	v_rcp_f32_e32 v67, v64
	v_cvt_pk_bf16_f32 v64, v72, v73
	v_rcp_f32_e32 v69, v69
	v_rcp_f32_e32 v74, v65
	v_cvt_pk_bf16_f32 v65, v68, v69
	v_cvt_pk_bf16_f32 v66, v70, v71
	v_cvt_pk_bf16_f32 v67, v67, v74
	global_store_dwordx4 v[76:77], v[64:67], off offset:256
	s_nop 1
	v_mul_f32_e32 v64, 0xbfb8aa3b, v138
	v_mul_f32_e32 v60, v60, v64
	v_mul_f32_e32 v61, v61, v64
	v_mul_f32_e32 v62, v62, v64
	v_mul_f32_e32 v63, v63, v64
	v_exp_f32_e32 v60, v60
	v_exp_f32_e32 v61, v61
	v_exp_f32_e32 v62, v62
	v_exp_f32_e32 v63, v63
	v_add_f32_e32 v60, 1.0, v60
	v_add_f32_e32 v61, 1.0, v61
	s_nop 0
	v_rcp_f32_e32 v65, v60
	v_rcp_f32_e32 v66, v61
	v_add_f32_e32 v60, 1.0, v62
	v_add_f32_e32 v61, 1.0, v63
	v_mul_f32_e32 v56, v56, v64
	v_mul_f32_e32 v57, v57, v64
	s_nop 0
	v_exp_f32_e32 v56, v56
	v_exp_f32_e32 v57, v57
	v_mul_f32_e32 v58, v58, v64
	v_mul_f32_e32 v59, v59, v64
	v_mul_f32_e32 v52, v52, v64
	v_mul_f32_e32 v53, v53, v64
	v_exp_f32_e32 v58, v58
	v_exp_f32_e32 v59, v59
	v_mul_f32_e32 v48, v48, v64
	v_mul_f32_e32 v49, v49, v64
	v_exp_f32_e32 v52, v52
	v_exp_f32_e32 v53, v53
	v_mul_f32_e32 v54, v54, v64
	v_mul_f32_e32 v55, v55, v64
	v_exp_f32_e32 v48, v48
	v_exp_f32_e32 v49, v49
	v_mul_f32_e32 v50, v50, v64
	v_mul_f32_e32 v51, v51, v64
	v_add_f32_e32 v56, 1.0, v56
	v_add_f32_e32 v57, 1.0, v57
	v_exp_f32_e32 v54, v54
	v_exp_f32_e32 v55, v55
	v_exp_f32_e32 v50, v50
	v_exp_f32_e32 v51, v51
	v_rcp_f32_e32 v60, v60
	v_rcp_f32_e32 v61, v61
	v_rcp_f32_e32 v62, v56
	v_rcp_f32_e32 v63, v57
	v_add_f32_e32 v56, 1.0, v58
	v_add_f32_e32 v57, 1.0, v59
	v_add_f32_e32 v52, 1.0, v52
	v_add_f32_e32 v53, 1.0, v53
	v_rcp_f32_e32 v59, v56
	v_rcp_f32_e32 v67, v57
	v_cvt_pk_bf16_f32 v56, v65, v66
	v_cvt_pk_bf16_f32 v57, v60, v61
	v_mad_i64_i32 v[60:61], s[2:3], v178, s41, v[120:121]
	v_lshl_add_u64 v[60:61], v[60:61], 0, v[122:123]
	v_add_f32_e32 v48, 1.0, v48
	v_add_f32_e32 v49, 1.0, v49
	v_cvt_pk_bf16_f32 v58, v62, v63
	v_cvt_pk_bf16_f32 v59, v59, v67
	global_store_dwordx4 v[60:61], v[56:59], off
	s_nop 1
	v_rcp_f32_e32 v56, v52
	v_rcp_f32_e32 v57, v53
	v_add_f32_e32 v52, 1.0, v54
	v_add_f32_e32 v53, 1.0, v55
	v_rcp_f32_e32 v54, v48
	v_rcp_f32_e32 v55, v49
	v_add_f32_e32 v48, 1.0, v50
	v_add_f32_e32 v49, 1.0, v51
	v_rcp_f32_e32 v52, v52
	v_rcp_f32_e32 v51, v48
	v_cvt_pk_bf16_f32 v48, v56, v57
	v_rcp_f32_e32 v53, v53
	v_rcp_f32_e32 v58, v49
	v_cvt_pk_bf16_f32 v49, v52, v53
	v_cvt_pk_bf16_f32 v50, v54, v55
	v_cvt_pk_bf16_f32 v51, v51, v58
	global_store_dwordx4 v[60:61], v[48:51], off offset:256
	s_nop 1
	v_mul_f32_e32 v48, 0xbfb8aa3b, v130
	v_mul_f32_e32 v44, v44, v48
	v_mul_f32_e32 v45, v45, v48
	v_mul_f32_e32 v46, v46, v48
	v_mul_f32_e32 v47, v47, v48
	v_exp_f32_e32 v44, v44
	v_exp_f32_e32 v45, v45
	v_exp_f32_e32 v46, v46
	v_exp_f32_e32 v47, v47
	v_add_f32_e32 v44, 1.0, v44
	v_add_f32_e32 v45, 1.0, v45
	s_nop 0
	v_rcp_f32_e32 v49, v44
	v_rcp_f32_e32 v50, v45
	v_add_f32_e32 v44, 1.0, v46
	v_add_f32_e32 v45, 1.0, v47
	v_mul_f32_e32 v40, v40, v48
	v_mul_f32_e32 v41, v41, v48
	s_nop 0
	v_exp_f32_e32 v40, v40
	v_exp_f32_e32 v41, v41
	v_mul_f32_e32 v42, v42, v48
	v_mul_f32_e32 v43, v43, v48
	v_mul_f32_e32 v36, v36, v48
	v_mul_f32_e32 v37, v37, v48
; __device__ __forceinline__ unsigned cvt_pk_bf16(float lo, float hi) { unsigned r; asm volatile("v_cvt_pk_bf16_f32 %0, %1, %2" : "=v"(r) : "v"(lo), "v"(hi)); return r; }
;     template <bool GATE> __device__ __forceinline__ void body(const f32x4 (&acc)[2][2][4][2], const Unit& u, int wr, int wc, int fr, int fq) const {
;     ...
;                 const int row = row0 + ai * HALF + m * 16; const float r = rs[ai][m], nrl = r * -1.44269504089f;
; #pragma unroll
;                 for (int bj = 0; bj < 2; ++bj) {
;                     unsigned pk[4];
; #pragma unroll
;                     for (int q = 0; q < 4; ++q) {
;                         const f32x4 va = acc[ai][bj][m][q >> 1]; const int e0 = 2 * (q & 1);
;                         const f32x2 v = (f32x2){va[e0], va[e0 + 1]};
;                         f32x2 o;
;                         if (GATE) { const f32x2 t = v * nrl; f32x2 ex; ex.x = __builtin_amdgcn_exp2f(t.x); ex.y = __builtin_amdgcn_exp2f(t.y);
;                             const f32x2 d = ex + 1.0f; o.x = __builtin_amdgcn_rcpf(d.x); o.y = __builtin_amdgcn_rcpf(d.y); }
;                         else o = v * r;
;                         pk[q] = cvt_pk_bf16(o.x, o.y);
;                     }
;                     u32x4 w; w.x = pk[0]; w.y = pk[1]; w.z = pk[2]; w.w = pk[3];
;                     *(u32x4*)(P + (size_t)row * PITCH + col0 + bj * HALF) = w;
	v_exp_f32_e32 v42, v42
	v_exp_f32_e32 v43, v43
	v_mul_f32_e32 v32, v32, v48
	v_mul_f32_e32 v33, v33, v48
	v_exp_f32_e32 v36, v36
	v_exp_f32_e32 v37, v37
	v_mul_f32_e32 v38, v38, v48
	v_mul_f32_e32 v39, v39, v48
	v_exp_f32_e32 v32, v32
	v_exp_f32_e32 v33, v33
	v_mul_f32_e32 v34, v34, v48
	v_mul_f32_e32 v35, v35, v48
	v_add_f32_e32 v40, 1.0, v40
	v_add_f32_e32 v41, 1.0, v41
	v_exp_f32_e32 v38, v38
	v_exp_f32_e32 v39, v39
	v_exp_f32_e32 v34, v34
	v_exp_f32_e32 v35, v35
	v_rcp_f32_e32 v44, v44
	v_rcp_f32_e32 v45, v45
	v_rcp_f32_e32 v46, v40
	v_rcp_f32_e32 v47, v41
	v_add_f32_e32 v40, 1.0, v42
	v_add_f32_e32 v41, 1.0, v43
	v_add_f32_e32 v36, 1.0, v36
	v_add_f32_e32 v37, 1.0, v37
	v_rcp_f32_e32 v43, v40
	v_rcp_f32_e32 v51, v41
	v_cvt_pk_bf16_f32 v40, v49, v50
	v_cvt_pk_bf16_f32 v41, v44, v45
	v_mad_i64_i32 v[44:45], s[2:3], v176, s41, v[120:121]
	v_lshl_add_u64 v[44:45], v[44:45], 0, v[122:123]
	v_add_f32_e32 v32, 1.0, v32
	v_add_f32_e32 v33, 1.0, v33
	v_cvt_pk_bf16_f32 v42, v46, v47
	v_cvt_pk_bf16_f32 v43, v43, v51
	global_store_dwordx4 v[44:45], v[40:43], off
	s_nop 1
	v_rcp_f32_e32 v40, v36
	v_rcp_f32_e32 v41, v37
	v_add_f32_e32 v36, 1.0, v38
	v_add_f32_e32 v37, 1.0, v39
	v_rcp_f32_e32 v38, v32
	v_rcp_f32_e32 v39, v33
	v_add_f32_e32 v32, 1.0, v34
	v_add_f32_e32 v33, 1.0, v35
	v_rcp_f32_e32 v36, v36
	v_rcp_f32_e32 v35, v32
	v_cvt_pk_bf16_f32 v32, v40, v41
	v_rcp_f32_e32 v37, v37
	v_rcp_f32_e32 v42, v33
	v_cvt_pk_bf16_f32 v33, v36, v37
	v_cvt_pk_bf16_f32 v34, v38, v39
	v_cvt_pk_bf16_f32 v35, v35, v42
	global_store_dwordx4 v[44:45], v[32:35], off offset:256
	s_nop 1
	v_mul_f32_e32 v32, 0xbfb8aa3b, v129
	v_mul_f32_e32 v28, v28, v32
	v_mul_f32_e32 v29, v29, v32
	v_mul_f32_e32 v30, v30, v32
	v_mul_f32_e32 v31, v31, v32
	v_exp_f32_e32 v28, v28
	v_exp_f32_e32 v29, v29
	v_exp_f32_e32 v30, v30
	v_exp_f32_e32 v31, v31
	v_add_f32_e32 v28, 1.0, v28
	v_add_f32_e32 v29, 1.0, v29
	s_nop 0
	v_rcp_f32_e32 v33, v28
	v_rcp_f32_e32 v34, v29
	v_add_f32_e32 v28, 1.0, v30
	v_add_f32_e32 v29, 1.0, v31
	v_mul_f32_e32 v24, v24, v32
	v_mul_f32_e32 v25, v25, v32
	s_nop 0
	v_exp_f32_e32 v24, v24
	v_exp_f32_e32 v25, v25
	v_mul_f32_e32 v26, v26, v32
	v_mul_f32_e32 v27, v27, v32
	v_mul_f32_e32 v20, v20, v32
	v_mul_f32_e32 v21, v21, v32
	v_exp_f32_e32 v26, v26
	v_exp_f32_e32 v27, v27
	v_mul_f32_e32 v16, v16, v32
	v_mul_f32_e32 v17, v17, v32
	v_exp_f32_e32 v20, v20
	v_exp_f32_e32 v21, v21
	v_mul_f32_e32 v22, v22, v32
	v_mul_f32_e32 v23, v23, v32
	v_exp_f32_e32 v16, v16
	v_exp_f32_e32 v17, v17
	v_mul_f32_e32 v18, v18, v32
	v_mul_f32_e32 v19, v19, v32
	v_add_f32_e32 v24, 1.0, v24
	v_add_f32_e32 v25, 1.0, v25
	v_exp_f32_e32 v22, v22
	v_exp_f32_e32 v23, v23
	v_exp_f32_e32 v18, v18
	v_exp_f32_e32 v19, v19
	v_rcp_f32_e32 v28, v28
	v_rcp_f32_e32 v29, v29
	v_rcp_f32_e32 v30, v24
	v_rcp_f32_e32 v31, v25
	v_add_f32_e32 v24, 1.0, v26
	v_add_f32_e32 v25, 1.0, v27
	v_add_f32_e32 v20, 1.0, v20
	v_add_f32_e32 v21, 1.0, v21
	v_rcp_f32_e32 v27, v24
	v_rcp_f32_e32 v35, v25
	v_cvt_pk_bf16_f32 v24, v33, v34
	v_cvt_pk_bf16_f32 v25, v28, v29
	v_mad_i64_i32 v[28:29], s[2:3], v174, s41, v[120:121]
	v_lshl_add_u64 v[28:29], v[28:29], 0, v[122:123]
	v_add_f32_e32 v16, 1.0, v16
	v_add_f32_e32 v17, 1.0, v17
	v_cvt_pk_bf16_f32 v26, v30, v31
	v_cvt_pk_bf16_f32 v27, v27, v35
	global_store_dwordx4 v[28:29], v[24:27], off
	s_nop 1
	v_rcp_f32_e32 v24, v20
	v_rcp_f32_e32 v25, v21
	v_add_f32_e32 v20, 1.0, v22
	v_add_f32_e32 v21, 1.0, v23
	v_rcp_f32_e32 v22, v16
	v_rcp_f32_e32 v23, v17
	v_add_f32_e32 v16, 1.0, v18
	v_add_f32_e32 v17, 1.0, v19
	v_rcp_f32_e32 v20, v20
	v_rcp_f32_e32 v19, v16
	v_cvt_pk_bf16_f32 v16, v24, v25
	v_rcp_f32_e32 v21, v21
	v_rcp_f32_e32 v26, v17
	v_cvt_pk_bf16_f32 v17, v20, v21
	v_cvt_pk_bf16_f32 v18, v22, v23
	v_cvt_pk_bf16_f32 v19, v19, v26
	global_store_dwordx4 v[28:29], v[16:19], off offset:256
	s_nop 1
	v_mul_f32_e32 v16, 0xbfb8aa3b, v128
	v_mul_f32_e32 v12, v12, v16
	v_mul_f32_e32 v13, v13, v16
	v_mul_f32_e32 v14, v14, v16
	v_mul_f32_e32 v15, v15, v16
	v_exp_f32_e32 v12, v12
	v_exp_f32_e32 v13, v13
	v_exp_f32_e32 v14, v14
	v_exp_f32_e32 v15, v15
	v_add_f32_e32 v12, 1.0, v12
	v_add_f32_e32 v13, 1.0, v13
	s_nop 0
	v_rcp_f32_e32 v17, v12
	v_rcp_f32_e32 v18, v13
	v_add_f32_e32 v12, 1.0, v14
	v_add_f32_e32 v13, 1.0, v15
	v_mul_f32_e32 v8, v8, v16
	v_mul_f32_e32 v9, v9, v16
	s_nop 0
	v_exp_f32_e32 v8, v8
	v_exp_f32_e32 v9, v9
	v_mul_f32_e32 v10, v10, v16
	v_mul_f32_e32 v11, v11, v16
	v_mul_f32_e32 v4, v4, v16
	v_mul_f32_e32 v5, v5, v16
	v_exp_f32_e32 v10, v10
	v_exp_f32_e32 v11, v11
	v_mul_f32_e32 v0, v0, v16
	v_mul_f32_e32 v1, v1, v16
	v_exp_f32_e32 v4, v4
	v_exp_f32_e32 v5, v5
	v_mul_f32_e32 v6, v6, v16
	v_mul_f32_e32 v7, v7, v16
	v_exp_f32_e32 v0, v0
	v_exp_f32_e32 v1, v1
	v_mul_f32_e32 v2, v2, v16
	v_mul_f32_e32 v3, v3, v16
	v_add_f32_e32 v8, 1.0, v8
	v_add_f32_e32 v9, 1.0, v9
	v_exp_f32_e32 v6, v6
	v_exp_f32_e32 v7, v7
	v_exp_f32_e32 v2, v2
	v_exp_f32_e32 v3, v3
	v_rcp_f32_e32 v12, v12
	v_rcp_f32_e32 v13, v13
	v_rcp_f32_e32 v14, v8
	v_rcp_f32_e32 v15, v9
	v_add_f32_e32 v8, 1.0, v10
	v_add_f32_e32 v9, 1.0, v11
	v_add_f32_e32 v4, 1.0, v4
	v_add_f32_e32 v5, 1.0, v5
	v_rcp_f32_e32 v11, v8
	v_rcp_f32_e32 v19, v9
	v_cvt_pk_bf16_f32 v8, v17, v18
	v_cvt_pk_bf16_f32 v9, v12, v13
	v_mad_i64_i32 v[12:13], s[2:3], v170, s41, v[120:121]
	v_lshl_add_u64 v[12:13], v[12:13], 0, v[122:123]
	v_add_f32_e32 v0, 1.0, v0
	v_add_f32_e32 v1, 1.0, v1
	v_cvt_pk_bf16_f32 v10, v14, v15
	v_cvt_pk_bf16_f32 v11, v11, v19
	global_store_dwordx4 v[12:13], v[8:11], off
	s_nop 1
	v_rcp_f32_e32 v8, v4
	v_rcp_f32_e32 v9, v5
	v_add_f32_e32 v4, 1.0, v6
	v_add_f32_e32 v5, 1.0, v7
	v_rcp_f32_e32 v6, v0
	v_rcp_f32_e32 v7, v1
	v_add_f32_e32 v0, 1.0, v2
	v_add_f32_e32 v1, 1.0, v3
	v_rcp_f32_e32 v4, v4
	v_rcp_f32_e32 v5, v5
	v_rcp_f32_e32 v0, v0
	v_rcp_f32_e32 v1, v1
	v_cvt_pk_bf16_f32 v148, v8, v9
	v_cvt_pk_bf16_f32 v149, v4, v5
	v_cvt_pk_bf16_f32 v150, v6, v7
	v_cvt_pk_bf16_f32 v151, v0, v1

; template <int NP> __device__ __forceinline__ void load_rs(const float* ssp, int row0, int fq, float (&rs)[2][4]) {
;     ...
;             for (int m = 0; m < 4; ++m) p[ai][m] = *(const f32x4*)(ssp + (size_t)(row0 + ai * HALF + m * 16) * 16 + 4 * fq);
; #pragma unroll
;         for (int ai = 0; ai < 2; ++ai)
; #pragma unroll
;             for (int m = 0; m < 4; ++m) { float s = (p[ai][m][0] + p[ai][m][1]) + (p[ai][m][2] + p[ai][m][3]); s += __shfl_xor(s, 16); s += __shfl_xor(s, 32); rs[ai][m] = s; }
;     __device__ __forceinline__ void operator()(const f32x4 (&acc)[2][2][4][2], const Unit& u, int wr, int wc, int fr, int fq) const {
;         const int row0 = u.pm * BM + wr * 64 + fr, col0 = u.pn * HALF + wc * 32 + 8 * fq;
;         float rs[2][4]; load_rs<NP>(ssp, row0, fq, rs);
; #pragma unroll
;         for (int ai = 0; ai < 2; ++ai)
; #pragma unroll
;             for (int m = 0; m < 4; ++m) {
;                 const int row = row0 + ai * HALF + m * 16; const float r = rs[ai][m];
;                 const float nrl = r * -1.44269504089f, r2 = r * r;
;                 unsigned pk[4];
; #pragma unroll
;                 for (int q = 0; q < 4; ++q) {
;                     const f32x4 ga = acc[ai][0][m][q >> 1], ua = acc[ai][1][m][q >> 1]; const int e0 = 2 * (q & 1);
;                     const f32x2 g = (f32x2){ga[e0], ga[e0 + 1]}, up = (f32x2){ua[e0], ua[e0 + 1]};
;                     const f32x2 t = g * nrl; f32x2 ex; ex.x = __builtin_amdgcn_exp2f(t.x); ex.y = __builtin_amdgcn_exp2f(t.y);
;                     const f32x2 d = ex + 1.0f; f32x2 rc; rc.x = __builtin_amdgcn_rcpf(d.x); rc.y = __builtin_amdgcn_rcpf(d.y);
;                     const f32x2 o = (g * up) * (rc * r2);
.LBB0_932:
	s_lshl_b32 s2, s41, 8
	s_add_i32 s2, s2, s29
	v_or_b32_e32 v146, s2, v150
	v_ashrrev_i32_e32 v147, 31, v146
	v_or_b32_e32 v160, 16, v146
	v_lshlrev_b64 v[148:149], 6, v[146:147]
	v_ashrrev_i32_e32 v161, 31, v160
	v_or_b32_e32 v168, 32, v146
	v_or_b32_e32 v170, 48, v146
	v_add_u32_e32 v146, 0x80, v146
	v_lshlrev_b64 v[160:161], 6, v[160:161]
	v_ashrrev_i32_e32 v169, 31, v168
	v_ashrrev_i32_e32 v171, 31, v170
	v_ashrrev_i32_e32 v147, 31, v146
	v_lshl_add_u64 v[148:149], v[138:139], 0, v[148:149]
	v_lshl_add_u64 v[164:165], v[138:139], 0, v[160:161]
	v_lshlrev_b64 v[168:169], 6, v[168:169]
	v_lshlrev_b64 v[170:171], 6, v[170:171]
	v_lshlrev_b64 v[176:177], 6, v[146:147]
	global_load_dwordx4 v[160:163], v[148:149], off
	s_nop 0
	global_load_dwordx4 v[164:167], v[164:165], off
	v_lshl_add_u64 v[168:169], v[138:139], 0, v[168:169]
	v_lshl_add_u64 v[172:173], v[138:139], 0, v[170:171]
	v_lshl_add_u64 v[176:177], v[138:139], 0, v[176:177]
	global_load_dwordx4 v[168:171], v[168:169], off
	s_nop 0
	global_load_dwordx4 v[172:175], v[172:173], off
	v_add_co_u32_e32 v148, vcc, s26, v148
	global_load_dwordx4 v[176:179], v[176:177], off
	s_nop 0
	v_addc_co_u32_e32 v149, vcc, 0, v149, vcc
	global_load_dwordx4 v[180:183], v[148:149], off offset:1024
	global_load_dwordx4 v[184:187], v[148:149], off offset:2048
	global_load_dwordx4 v[190:193], v[148:149], off offset:3072
	v_and_b32_e32 v147, 64, v156
	v_xor_b32_e32 v136, 16, v156
	v_add_u32_e32 v147, 64, v147
	v_xor_b32_e32 v149, 32, v156
	v_cmp_lt_i32_e32 vcc, v136, v147
	v_mul_f32_e32 v120, v124, v120
	v_mul_f32_e32 v121, v125, v121
	v_mul_f32_e32 v122, v126, v122
	v_mul_f32_e32 v123, v127, v123
	v_cndmask_b32_e32 v136, v156, v136, vcc
	v_cmp_lt_i32_e32 vcc, v149, v147
	v_lshlrev_b32_e32 v136, 2, v136
	v_mul_f32_e32 v112, v116, v112
	v_mul_f32_e32 v113, v117, v113
	v_cndmask_b32_e32 v147, v156, v149, vcc
	v_lshlrev_b32_e32 v147, 2, v147
	v_mul_f32_e32 v114, v118, v114
	v_mul_f32_e32 v115, v119, v115
	v_mul_f32_e32 v104, v108, v104
	v_mul_f32_e32 v105, v109, v105
	s_ashr_i32 s3, s2, 13
	s_mul_hi_i32 s11, s3, 0x4400000
	s_mul_i32 s3, s3, 0x4400000
	v_readlane_b32 s16, v235, 44
	v_lshl_or_b32 v148, s42, 7, v152
	v_readlane_b32 s17, v235, 45
	v_mul_f32_e32 v106, v110, v106
	v_mul_f32_e32 v107, v111, v107
	v_mul_f32_e32 v96, v100, v96
	v_mul_f32_e32 v97, v101, v97
	v_mul_f32_e32 v98, v102, v98
	v_mul_f32_e32 v99, v103, v99
	v_mul_f32_e32 v88, v92, v88
	v_mul_f32_e32 v89, v93, v89
	v_mul_f32_e32 v90, v94, v90
	v_mul_f32_e32 v91, v95, v91
	v_mul_f32_e32 v80, v84, v80
	v_mul_f32_e32 v81, v85, v81
	v_mul_f32_e32 v82, v86, v82
	v_mul_f32_e32 v83, v87, v83
	v_mul_f32_e32 v72, v76, v72
	v_mul_f32_e32 v73, v77, v73
	v_mul_f32_e32 v74, v78, v74
	v_mul_f32_e32 v75, v79, v75
	v_mul_f32_e32 v64, v68, v64
	v_mul_f32_e32 v65, v69, v65
	v_mul_f32_e32 v66, v70, v66
	v_mul_f32_e32 v67, v71, v67
	v_mul_f32_e32 v56, v60, v56
	v_mul_f32_e32 v57, v61, v57
	v_mul_f32_e32 v58, v62, v58
	v_mul_f32_e32 v59, v63, v59
	v_mul_f32_e32 v48, v52, v48
	v_mul_f32_e32 v49, v53, v49
	v_mul_f32_e32 v50, v54, v50
	v_mul_f32_e32 v51, v55, v51
	v_mul_f32_e32 v40, v44, v40
	v_mul_f32_e32 v41, v45, v41
	v_mul_f32_e32 v42, v46, v42
	v_mul_f32_e32 v43, v47, v43
	v_mul_f32_e32 v32, v36, v32
	v_mul_f32_e32 v33, v37, v33
	v_mul_f32_e32 v34, v38, v34
	v_mul_f32_e32 v35, v39, v35
	v_mul_f32_e32 v24, v28, v24
	v_mul_f32_e32 v25, v29, v25
	v_mul_f32_e32 v26, v30, v26
	v_mul_f32_e32 v27, v31, v27
	v_mul_f32_e32 v16, v20, v16
	v_mul_f32_e32 v17, v21, v17
	v_mul_f32_e32 v18, v22, v18
	v_mul_f32_e32 v19, v23, v19
	v_mul_f32_e32 v8, v12, v8
	v_mul_f32_e32 v9, v13, v9
	v_mul_f32_e32 v10, v14, v10
	v_mul_f32_e32 v11, v15, v11
	v_mul_f32_e32 v0, v4, v0
	v_mul_f32_e32 v1, v5, v1
	v_mul_f32_e32 v2, v6, v2
	v_mul_f32_e32 v3, v7, v3
	s_waitcnt vmcnt(0)
	v_mov_b32_e32 v194, v161
	v_mov_b32_e32 v195, v162
	v_mov_b32_e32 v161, v163
	v_add_f32_e32 v160, v194, v160
	v_add_f32_e32 v161, v195, v161
	v_mov_b32_e32 v162, v165
	v_mov_b32_e32 v163, v166
	v_mov_b32_e32 v165, v167
	v_mov_b32_e32 v166, v169
	v_mov_b32_e32 v167, v170
	v_mov_b32_e32 v169, v171
	v_mov_b32_e32 v170, v173
	v_mov_b32_e32 v171, v174
	v_mov_b32_e32 v173, v175
	v_mov_b32_e32 v174, v177
	v_mov_b32_e32 v175, v178
	v_mov_b32_e32 v177, v179
	v_add_f32_e32 v149, v160, v161
	v_add_f32_e32 v160, v162, v164
	v_add_f32_e32 v161, v163, v165
	v_add_f32_e32 v162, v166, v168
	v_add_f32_e32 v163, v167, v169
	v_add_f32_e32 v166, v174, v176
	v_add_f32_e32 v167, v175, v177
	v_add_f32_e32 v160, v160, v161
	v_add_f32_e32 v161, v162, v163
	v_mov_b32_e32 v236, v149
	v_mov_b32_e32 v237, v149
	s_nop 1
	v_permlane16_swap_b32_e32 v236, v237
	v_cndmask_b32_e64 v159, v237, v236, s[98:99]
	v_add_f32_e32 v163, v166, v167
	v_mov_b32_e32 v236, v160
	v_mov_b32_e32 v237, v160
	s_nop 1
	v_permlane16_swap_b32_e32 v236, v237
	v_cndmask_b32_e64 v166, v237, v236, s[98:99]
	v_mov_b32_e32 v236, v161
	v_mov_b32_e32 v237, v161
	s_nop 1
	v_permlane16_swap_b32_e32 v236, v237
	v_cndmask_b32_e64 v167, v237, v236, s[98:99]
	v_mov_b32_e32 v178, v181
	s_waitcnt lgkmcnt(2)
	v_add_f32_e32 v149, v149, v159
	v_mov_b32_e32 v236, v149
	v_mov_b32_e32 v237, v149
	s_nop 1
	v_permlane32_swap_b32_e32 v236, v237
	v_cndmask_b32_e64 v159, v237, v236, s[100:101]
	s_waitcnt lgkmcnt(2)
	v_add_f32_e32 v160, v160, v166
	s_waitcnt lgkmcnt(1)
; __device__ __forceinline__ unsigned cvt_pk_bf16(float lo, float hi) { unsigned r; asm volatile("v_cvt_pk_bf16_f32 %0, %1, %2" : "=v"(r) : "v"(lo), "v"(hi)); return r; }
; template <int NP> __device__ __forceinline__ void load_rs(const float* ssp, int row0, int fq, float (&rs)[2][4]) {
;     ...
;             for (int m = 0; m < 4; ++m) { float s = (p[ai][m][0] + p[ai][m][1]) + (p[ai][m][2] + p[ai][m][3]); s += __shfl_xor(s, 16); s += __shfl_xor(s, 32); rs[ai][m] = s; }
;     }
; #pragma unroll
;     for (int ai = 0; ai < 2; ++ai)
; #pragma unroll
;         for (int m = 0; m < 4; ++m) rs[ai][m] = __builtin_amdgcn_rsqf(rs[ai][m] * (1.0f / D_MODEL) + RMS_EPS);
;     __device__ __forceinline__ void operator()(const f32x4 (&acc)[2][2][4][2], const Unit& u, int wr, int wc, int fr, int fq) const {
;     ...
;                 const int row = row0 + ai * HALF + m * 16; const float r = rs[ai][m];
;                 const float nrl = r * -1.44269504089f, r2 = r * r;
;                 unsigned pk[4];
; #pragma unroll
;                 for (int q = 0; q < 4; ++q) {
;                     const f32x4 ga = acc[ai][0][m][q >> 1], ua = acc[ai][1][m][q >> 1]; const int e0 = 2 * (q & 1);
;                     const f32x2 g = (f32x2){ga[e0], ga[e0 + 1]}, up = (f32x2){ua[e0], ua[e0 + 1]};
;                     const f32x2 t = g * nrl; f32x2 ex; ex.x = __builtin_amdgcn_exp2f(t.x); ex.y = __builtin_amdgcn_exp2f(t.y);
;                     const f32x2 d = ex + 1.0f; f32x2 rc; rc.x = __builtin_amdgcn_rcpf(d.x); rc.y = __builtin_amdgcn_rcpf(d.y);
;                     const f32x2 o = (g * up) * (rc * r2);
;                     pk[q] = cvt_pk_bf16(o.x, o.y);
;                 }
;                 u32x4 w; w.x = pk[0]; w.y = pk[1]; w.z = pk[2]; w.w = pk[3];
;                 *(u32x4*)(U + (size_t)(row >> 13) * U_SLAB + (size_t)(row & (SEQ - 1)) * U_PITCH + col0) = w;
	v_add_f32_e32 v161, v161, v167
	v_mov_b32_e32 v236, v160
	v_mov_b32_e32 v237, v160
	s_nop 1
	v_permlane32_swap_b32_e32 v236, v237
	v_cndmask_b32_e64 v166, v237, v236, s[100:101]
	v_mov_b32_e32 v236, v161
	v_mov_b32_e32 v237, v161
	s_nop 1
	v_permlane32_swap_b32_e32 v236, v237
	v_cndmask_b32_e64 v167, v237, v236, s[100:101]
	v_mov_b32_e32 v179, v182
	v_mov_b32_e32 v181, v183
	v_mov_b32_e32 v182, v185
	v_mov_b32_e32 v183, v186
	v_mov_b32_e32 v185, v187
	v_mov_b32_e32 v186, v191
	v_mov_b32_e32 v187, v192
	v_mov_b32_e32 v191, v193
	v_add_f32_e32 v164, v170, v172
	v_add_f32_e32 v165, v171, v173
	v_add_f32_e32 v168, v178, v180
	v_add_f32_e32 v169, v179, v181
	v_add_f32_e32 v170, v182, v184
	v_add_f32_e32 v171, v183, v185
	s_waitcnt lgkmcnt(2)
	v_add_f32_e32 v149, v149, v159
	s_waitcnt lgkmcnt(1)
	v_add_f32_e32 v159, v160, v166
	s_waitcnt lgkmcnt(0)
	v_add_f32_e32 v166, v161, v167
	v_add_f32_e32 v160, v186, v190
	v_add_f32_e32 v161, v187, v191
	v_add_f32_e32 v162, v164, v165
	v_add_f32_e32 v164, v168, v169
	v_add_f32_e32 v165, v170, v171
	v_add_f32_e32 v160, v160, v161
	v_mov_b32_e32 v236, v162
	v_mov_b32_e32 v237, v162
	s_nop 1
	v_permlane16_swap_b32_e32 v236, v237
	v_cndmask_b32_e64 v168, v237, v236, s[98:99]
	v_mov_b32_e32 v236, v163
	v_mov_b32_e32 v237, v163
	s_nop 1
	v_permlane16_swap_b32_e32 v236, v237
	v_cndmask_b32_e64 v169, v237, v236, s[98:99]
	v_mov_b32_e32 v236, v164
	v_mov_b32_e32 v237, v164
	s_nop 1
	v_permlane16_swap_b32_e32 v236, v237
	v_cndmask_b32_e64 v170, v237, v236, s[98:99]
	v_mov_b32_e32 v236, v165
	v_mov_b32_e32 v237, v165
	s_nop 1
	v_permlane16_swap_b32_e32 v236, v237
	v_cndmask_b32_e64 v171, v237, v236, s[98:99]
	v_mov_b32_e32 v236, v160
	v_mov_b32_e32 v237, v160
	s_nop 1
	v_permlane16_swap_b32_e32 v236, v237
	v_cndmask_b32_e64 v136, v237, v236, s[98:99]
	s_waitcnt lgkmcnt(4)
	v_add_f32_e32 v162, v162, v168
	s_waitcnt lgkmcnt(3)
	v_add_f32_e32 v163, v163, v169
	s_waitcnt lgkmcnt(2)
	v_add_f32_e32 v161, v164, v170
	s_waitcnt lgkmcnt(1)
	v_add_f32_e32 v165, v165, v171
	s_waitcnt lgkmcnt(0)
	v_add_f32_e32 v136, v160, v136
	v_mov_b32_e32 v236, v162
	v_mov_b32_e32 v237, v162
	s_nop 1
	v_permlane32_swap_b32_e32 v236, v237
	v_cndmask_b32_e64 v168, v237, v236, s[100:101]
	v_mov_b32_e32 v236, v163
	v_mov_b32_e32 v237, v163
	s_nop 1
	v_permlane32_swap_b32_e32 v236, v237
	v_cndmask_b32_e64 v169, v237, v236, s[100:101]
	v_mov_b32_e32 v236, v161
	v_mov_b32_e32 v237, v161
	s_nop 1
	v_permlane32_swap_b32_e32 v236, v237
	v_cndmask_b32_e64 v164, v237, v236, s[100:101]
	v_mov_b32_e32 v236, v165
	v_mov_b32_e32 v237, v165
	s_nop 1
	v_permlane32_swap_b32_e32 v236, v237
	v_cndmask_b32_e64 v167, v237, v236, s[100:101]
	v_mov_b32_e32 v236, v136
	v_mov_b32_e32 v237, v136
	s_nop 1
	v_permlane32_swap_b32_e32 v236, v237
	v_cndmask_b32_e64 v147, v237, v236, s[100:101]
	s_waitcnt lgkmcnt(4)
	v_add_f32_e32 v160, v162, v168
	s_waitcnt lgkmcnt(3)
	v_add_f32_e32 v162, v163, v169
	s_waitcnt lgkmcnt(2)
	v_add_f32_e32 v161, v161, v164
	s_waitcnt lgkmcnt(1)
	v_add_f32_e32 v163, v165, v167
	s_waitcnt lgkmcnt(0)
	v_add_f32_e32 v136, v136, v147
	v_fmamk_f32 v147, v149, 0x3a800000, v157
	v_rsq_f32_e32 v164, v147
	v_fmamk_f32 v147, v159, 0x3a800000, v157
	v_rsq_f32_e32 v165, v147
	v_fmamk_f32 v147, v166, 0x3a800000, v157
	v_rsq_f32_e32 v166, v147
	v_fmamk_f32 v147, v160, 0x3a800000, v157
	v_rsq_f32_e32 v167, v147
	v_fmamk_f32 v147, v162, 0x3a800000, v157
	v_rsq_f32_e32 v168, v147
	v_fmamk_f32 v147, v161, 0x3a800000, v157
	v_rsq_f32_e32 v160, v147
	v_fmamk_f32 v147, v163, 0x3a800000, v157
	v_fmamk_f32 v136, v136, 0x3a800000, v157
	v_rsq_f32_e32 v159, v147
	v_rsq_f32_e32 v147, v136
	v_mul_f32_e32 v136, 0xbfb8aa3b, v164
	v_mul_f32_e32 v162, v124, v136
	v_mul_f32_e32 v163, v125, v136
	v_mul_f32_e32 v124, v126, v136
	v_mul_f32_e32 v125, v127, v136
	v_exp_f32_e32 v162, v162
	v_exp_f32_e32 v163, v163
	v_exp_f32_e32 v124, v124
	v_exp_f32_e32 v125, v125
	v_mul_f32_e32 v164, v164, v164
	v_add_f32_e32 v162, 1.0, v162
	v_add_f32_e32 v163, 1.0, v163
	v_bitop3_b32 v161, s2, v158, v150 bitop3:0xc8
	v_rcp_f32_e32 v162, v162
	v_rcp_f32_e32 v163, v163
	v_add_f32_e32 v124, 1.0, v124
	v_add_f32_e32 v125, 1.0, v125
	s_add_u32 s2, s16, s3
	v_rcp_f32_e32 v124, v124
	v_rcp_f32_e32 v125, v125
	v_mul_f32_e32 v126, v164, v162
	v_mul_f32_e32 v127, v164, v163
	v_mul_f32_e32 v120, v120, v126
	v_mul_f32_e32 v121, v121, v127
	v_mul_f32_e32 v126, v116, v136
	v_mul_f32_e32 v127, v117, v136
	v_mul_f32_e32 v124, v164, v124
	v_mul_f32_e32 v125, v164, v125
	v_exp_f32_e32 v126, v126
	v_exp_f32_e32 v127, v127
	v_mul_f32_e32 v122, v122, v124
	v_mul_f32_e32 v123, v123, v125
	v_mul_f32_e32 v124, v118, v136
	v_mul_f32_e32 v125, v119, v136
	v_cvt_pk_bf16_f32 v120, v120, v121
	v_cvt_pk_bf16_f32 v121, v122, v123
	v_add_f32_e32 v122, 1.0, v126
	v_add_f32_e32 v123, 1.0, v127
	v_exp_f32_e32 v124, v124
	v_exp_f32_e32 v125, v125
	v_rcp_f32_e32 v122, v122
	v_rcp_f32_e32 v123, v123
	v_ashrrev_i32_e32 v149, 31, v148
	v_add_f32_e32 v116, 1.0, v124
	v_add_f32_e32 v117, 1.0, v125
	s_addc_u32 s3, s17, s11
	v_rcp_f32_e32 v116, v116
	v_rcp_f32_e32 v117, v117
	v_mul_f32_e32 v118, v164, v122
	v_mul_f32_e32 v119, v164, v123
	v_mul_f32_e32 v112, v112, v118
	v_mul_f32_e32 v113, v113, v119
	s_nop 0
	v_cvt_pk_bf16_f32 v122, v112, v113
	v_mul_f32_e32 v112, v164, v116
	v_mul_f32_e32 v113, v164, v117
	v_mul_f32_e32 v116, 0xbfb8aa3b, v165
	v_mul_f32_e32 v118, v108, v116
	v_mul_f32_e32 v119, v109, v116
	v_mul_f32_e32 v108, v110, v116
	v_mul_f32_e32 v109, v111, v116
	v_exp_f32_e32 v118, v118
	v_exp_f32_e32 v119, v119
	v_exp_f32_e32 v108, v108
	v_exp_f32_e32 v109, v109
	v_mul_f32_e32 v112, v114, v112
	v_mul_f32_e32 v113, v115, v113
; __device__ __forceinline__ unsigned cvt_pk_bf16(float lo, float hi) { unsigned r; asm volatile("v_cvt_pk_bf16_f32 %0, %1, %2" : "=v"(r) : "v"(lo), "v"(hi)); return r; }
;     __device__ __forceinline__ void operator()(const f32x4 (&acc)[2][2][4][2], const Unit& u, int wr, int wc, int fr, int fq) const {
;     ...
;                 const int row = row0 + ai * HALF + m * 16; const float r = rs[ai][m];
;                 const float nrl = r * -1.44269504089f, r2 = r * r;
;                 unsigned pk[4];
; #pragma unroll
;                 for (int q = 0; q < 4; ++q) {
;                     const f32x4 ga = acc[ai][0][m][q >> 1], ua = acc[ai][1][m][q >> 1]; const int e0 = 2 * (q & 1);
;                     const f32x2 g = (f32x2){ga[e0], ga[e0 + 1]}, up = (f32x2){ua[e0], ua[e0 + 1]};
;                     const f32x2 t = g * nrl; f32x2 ex; ex.x = __builtin_amdgcn_exp2f(t.x); ex.y = __builtin_amdgcn_exp2f(t.y);
;                     const f32x2 d = ex + 1.0f; f32x2 rc; rc.x = __builtin_amdgcn_rcpf(d.x); rc.y = __builtin_amdgcn_rcpf(d.y);
;                     const f32x2 o = (g * up) * (rc * r2);
;                     pk[q] = cvt_pk_bf16(o.x, o.y);
;                 }
;                 u32x4 w; w.x = pk[0]; w.y = pk[1]; w.z = pk[2]; w.w = pk[3];
;                 *(u32x4*)(U + (size_t)(row >> 13) * U_SLAB + (size_t)(row & (SEQ - 1)) * U_PITCH + col0) = w;
	v_add_f32_e32 v118, 1.0, v118
	v_add_f32_e32 v119, 1.0, v119
	v_cvt_pk_bf16_f32 v123, v112, v113
	v_mul_u32_u24_e32 v112, 0xb40, v161
	v_lshlrev_b32_e32 v136, 1, v112
	v_rcp_f32_e32 v118, v118
	v_rcp_f32_e32 v119, v119
	v_lshl_add_u64 v[114:115], s[2:3], 0, v[136:137]
	v_lshlrev_b64 v[112:113], 1, v[148:149]
	v_add_f32_e32 v108, 1.0, v108
	v_add_f32_e32 v109, 1.0, v109
	v_lshl_add_u64 v[114:115], v[114:115], 0, v[112:113]
	v_rcp_f32_e32 v108, v108
	v_rcp_f32_e32 v109, v109
	global_store_dwordx4 v[114:115], v[120:123], off
	s_nop 1
	v_mul_f32_e32 v120, v165, v165
	v_mul_f32_e32 v110, v120, v118
	v_mul_f32_e32 v111, v120, v119
	v_mul_f32_e32 v104, v104, v110
	v_mul_f32_e32 v105, v105, v111
	v_mul_f32_e32 v110, v100, v116
	v_mul_f32_e32 v111, v101, v116
	v_mul_f32_e32 v108, v120, v108
	v_mul_f32_e32 v109, v120, v109
	v_exp_f32_e32 v110, v110
	v_exp_f32_e32 v111, v111
	v_mul_f32_e32 v106, v106, v108
	v_mul_f32_e32 v107, v107, v109
	v_mul_f32_e32 v108, v102, v116
	v_mul_f32_e32 v109, v103, v116
	v_cvt_pk_bf16_f32 v104, v104, v105
	v_cvt_pk_bf16_f32 v105, v106, v107
	v_add_f32_e32 v106, 1.0, v110
	v_add_f32_e32 v107, 1.0, v111
	v_exp_f32_e32 v108, v108
	v_exp_f32_e32 v109, v109
	v_rcp_f32_e32 v106, v106
	v_rcp_f32_e32 v107, v107
	v_add_f32_e32 v100, 1.0, v108
	v_add_f32_e32 v101, 1.0, v109
	s_nop 0
	v_rcp_f32_e32 v100, v100
	v_rcp_f32_e32 v101, v101
	v_mul_f32_e32 v102, v120, v106
	v_mul_f32_e32 v103, v120, v107
	v_mul_f32_e32 v96, v96, v102
	v_mul_f32_e32 v97, v97, v103
	s_nop 0
	v_cvt_pk_bf16_f32 v106, v96, v97
	v_mul_f32_e32 v96, v120, v100
	v_mul_f32_e32 v97, v120, v101
	v_mul_f32_e32 v96, v98, v96
	v_mul_f32_e32 v97, v99, v97
	v_add_co_u32_e32 v100, vcc, s28, v114
	v_cvt_pk_bf16_f32 v107, v96, v97
	v_mul_f32_e32 v96, 0xbfb8aa3b, v166
	v_mul_f32_e32 v98, v92, v96
	v_mul_f32_e32 v99, v93, v96
	v_mul_f32_e32 v92, v94, v96
	v_mul_f32_e32 v93, v95, v96
	v_exp_f32_e32 v98, v98
	v_exp_f32_e32 v99, v99
	v_exp_f32_e32 v92, v92
	v_exp_f32_e32 v93, v93
	v_addc_co_u32_e32 v101, vcc, 0, v115, vcc
	v_add_f32_e32 v98, 1.0, v98
	v_add_f32_e32 v99, 1.0, v99
	v_add_f32_e32 v92, 1.0, v92
	v_add_f32_e32 v93, 1.0, v93
	v_rcp_f32_e32 v98, v98
	v_rcp_f32_e32 v99, v99
	v_rcp_f32_e32 v92, v92
	v_rcp_f32_e32 v93, v93
	global_store_dwordx4 v[100:101], v[104:107], off offset:2048
	v_mul_f32_e32 v100, v166, v166
	v_mul_f32_e32 v94, v100, v98
	v_mul_f32_e32 v95, v100, v99
	v_mul_f32_e32 v88, v88, v94
	v_mul_f32_e32 v89, v89, v95
	v_mul_f32_e32 v94, v84, v96
	v_mul_f32_e32 v95, v85, v96
	v_mul_f32_e32 v92, v100, v92
	v_mul_f32_e32 v93, v100, v93
	v_exp_f32_e32 v94, v94
	v_exp_f32_e32 v95, v95
	v_mul_f32_e32 v90, v90, v92
	v_mul_f32_e32 v91, v91, v93
	v_mul_f32_e32 v92, v86, v96
	v_mul_f32_e32 v93, v87, v96
	v_cvt_pk_bf16_f32 v88, v88, v89
	v_cvt_pk_bf16_f32 v89, v90, v91
	v_add_f32_e32 v90, 1.0, v94
	v_add_f32_e32 v91, 1.0, v95
	v_exp_f32_e32 v92, v92
	v_exp_f32_e32 v93, v93
	v_rcp_f32_e32 v90, v90
	v_rcp_f32_e32 v91, v91
	v_add_f32_e32 v84, 1.0, v92
	v_add_f32_e32 v85, 1.0, v93
	s_nop 0
	v_rcp_f32_e32 v84, v84
	v_rcp_f32_e32 v85, v85
	v_mul_f32_e32 v86, v100, v90
	v_mul_f32_e32 v87, v100, v91
	v_mul_f32_e32 v80, v80, v86
	v_mul_f32_e32 v81, v81, v87
	s_nop 0
	v_cvt_pk_bf16_f32 v90, v80, v81
	v_mul_f32_e32 v80, v100, v84
	v_mul_f32_e32 v81, v100, v85
	v_mul_f32_e32 v80, v82, v80
	v_mul_f32_e32 v81, v83, v81
	v_add_co_u32_e32 v84, vcc, s38, v114
	v_cvt_pk_bf16_f32 v91, v80, v81
	v_mul_f32_e32 v80, 0xbfb8aa3b, v167
	v_mul_f32_e32 v82, v76, v80
	v_mul_f32_e32 v83, v77, v80
	v_mul_f32_e32 v76, v78, v80
	v_mul_f32_e32 v77, v79, v80
	v_exp_f32_e32 v82, v82
	v_exp_f32_e32 v83, v83
	v_exp_f32_e32 v76, v76
	v_exp_f32_e32 v77, v77
	v_addc_co_u32_e32 v85, vcc, 0, v115, vcc
	v_add_f32_e32 v82, 1.0, v82
	v_add_f32_e32 v83, 1.0, v83
	v_add_f32_e32 v76, 1.0, v76
	v_add_f32_e32 v77, 1.0, v77
	v_rcp_f32_e32 v82, v82
	v_rcp_f32_e32 v83, v83
	v_rcp_f32_e32 v76, v76
	v_rcp_f32_e32 v77, v77
	global_store_dwordx4 v[84:85], v[88:91], off
	v_mul_f32_e32 v84, v167, v167
	v_mul_f32_e32 v78, v84, v82
	v_mul_f32_e32 v79, v84, v83
	v_mul_f32_e32 v72, v72, v78
	v_mul_f32_e32 v73, v73, v79
	v_mul_f32_e32 v78, v68, v80
	v_mul_f32_e32 v79, v69, v80
	v_mul_f32_e32 v76, v84, v76
	v_mul_f32_e32 v77, v84, v77
	v_exp_f32_e32 v78, v78
	v_exp_f32_e32 v79, v79
	v_mul_f32_e32 v74, v74, v76
	v_mul_f32_e32 v75, v75, v77
	v_mul_f32_e32 v76, v70, v80
	v_mul_f32_e32 v77, v71, v80
	v_cvt_pk_bf16_f32 v72, v72, v73
	v_cvt_pk_bf16_f32 v73, v74, v75
	v_add_f32_e32 v74, 1.0, v78
	v_add_f32_e32 v75, 1.0, v79
	v_exp_f32_e32 v76, v76
	v_exp_f32_e32 v77, v77
	v_rcp_f32_e32 v74, v74
	v_rcp_f32_e32 v75, v75
	v_add_f32_e32 v68, 1.0, v76
	v_add_f32_e32 v69, 1.0, v77
	s_nop 0
	v_rcp_f32_e32 v68, v68
	v_rcp_f32_e32 v69, v69
	v_mul_f32_e32 v70, v84, v74
	v_mul_f32_e32 v71, v84, v75
	v_mul_f32_e32 v64, v64, v70
	v_mul_f32_e32 v65, v65, v71
	s_nop 0
	v_cvt_pk_bf16_f32 v74, v64, v65
	v_mul_f32_e32 v64, v84, v68
	v_mul_f32_e32 v65, v84, v69
	v_mul_f32_e32 v64, v66, v64
	v_mul_f32_e32 v65, v67, v65
	v_and_b32_e32 v69, 0x1fcf, v146
	v_cvt_pk_bf16_f32 v75, v64, v65
	v_add_co_u32_e32 v64, vcc, s39, v114
	v_mul_f32_e32 v68, v168, v168
	s_nop 0
	v_addc_co_u32_e32 v65, vcc, 0, v115, vcc
	global_store_dwordx4 v[64:65], v[72:75], off offset:2048
	v_mul_f32_e32 v64, 0xbfb8aa3b, v168
	v_mul_f32_e32 v66, v60, v64
	v_mul_f32_e32 v67, v61, v64
	v_ashrrev_i32_e32 v65, 13, v146
	v_exp_f32_e32 v66, v66
	v_exp_f32_e32 v67, v67
	v_mul_f32_e32 v60, v62, v64
	v_mul_f32_e32 v61, v63, v64
	v_add_f32_e32 v66, 1.0, v66
	v_add_f32_e32 v67, 1.0, v67
	v_exp_f32_e32 v60, v60
	v_exp_f32_e32 v61, v61
	v_rcp_f32_e32 v66, v66
	v_rcp_f32_e32 v67, v67
; __device__ __forceinline__ unsigned cvt_pk_bf16(float lo, float hi) { unsigned r; asm volatile("v_cvt_pk_bf16_f32 %0, %1, %2" : "=v"(r) : "v"(lo), "v"(hi)); return r; }
;     __device__ __forceinline__ void operator()(const f32x4 (&acc)[2][2][4][2], const Unit& u, int wr, int wc, int fr, int fq) const {
;     ...
;                 const int row = row0 + ai * HALF + m * 16; const float r = rs[ai][m];
;                 const float nrl = r * -1.44269504089f, r2 = r * r;
;                 unsigned pk[4];
; #pragma unroll
;                 for (int q = 0; q < 4; ++q) {
;                     const f32x4 ga = acc[ai][0][m][q >> 1], ua = acc[ai][1][m][q >> 1]; const int e0 = 2 * (q & 1);
;                     const f32x2 g = (f32x2){ga[e0], ga[e0 + 1]}, up = (f32x2){ua[e0], ua[e0 + 1]};
;                     const f32x2 t = g * nrl; f32x2 ex; ex.x = __builtin_amdgcn_exp2f(t.x); ex.y = __builtin_amdgcn_exp2f(t.y);
;                     const f32x2 d = ex + 1.0f; f32x2 rc; rc.x = __builtin_amdgcn_rcpf(d.x); rc.y = __builtin_amdgcn_rcpf(d.y);
;                     const f32x2 o = (g * up) * (rc * r2);
;                     pk[q] = cvt_pk_bf16(o.x, o.y);
;                 }
;                 u32x4 w; w.x = pk[0]; w.y = pk[1]; w.z = pk[2]; w.w = pk[3];
;                 *(u32x4*)(U + (size_t)(row >> 13) * U_SLAB + (size_t)(row & (SEQ - 1)) * U_PITCH + col0) = w;
	v_add_f32_e32 v60, 1.0, v60
	v_add_f32_e32 v61, 1.0, v61
	s_nop 0
	v_rcp_f32_e32 v60, v60
	v_rcp_f32_e32 v61, v61
	v_mul_f32_e32 v62, v68, v66
	v_mul_f32_e32 v63, v68, v67
	v_mul_f32_e32 v56, v56, v62
	v_mul_f32_e32 v57, v57, v63
	v_mul_f32_e32 v62, v52, v64
	v_mul_f32_e32 v63, v53, v64
	v_mul_f32_e32 v60, v68, v60
	v_mul_f32_e32 v61, v68, v61
	v_exp_f32_e32 v62, v62
	v_exp_f32_e32 v63, v63
	v_mul_f32_e32 v58, v58, v60
	v_mul_f32_e32 v59, v59, v61
	v_mul_f32_e32 v60, v54, v64
	v_mul_f32_e32 v61, v55, v64
	v_cvt_pk_bf16_f32 v56, v56, v57
	v_cvt_pk_bf16_f32 v57, v58, v59
	v_add_f32_e32 v58, 1.0, v62
	v_add_f32_e32 v59, 1.0, v63
	v_exp_f32_e32 v60, v60
	v_exp_f32_e32 v61, v61
	v_rcp_f32_e32 v58, v58
	v_rcp_f32_e32 v59, v59
	v_add_f32_e32 v52, 1.0, v60
	v_add_f32_e32 v53, 1.0, v61
	s_nop 0
	v_rcp_f32_e32 v52, v52
	v_rcp_f32_e32 v53, v53
	v_mul_f32_e32 v54, v68, v58
	v_mul_f32_e32 v55, v68, v59
	v_mul_f32_e32 v48, v48, v54
	v_mul_f32_e32 v49, v49, v55
	v_mul_f32_e32 v54, v160, v160
	v_cvt_pk_bf16_f32 v58, v48, v49
	v_mul_f32_e32 v48, v68, v52
	v_mul_f32_e32 v49, v68, v53
	v_mul_f32_e32 v48, v50, v48
	v_mul_f32_e32 v49, v51, v49
	v_mul_u32_u24_e32 v50, 0xb40, v69
	v_lshlrev_b32_e32 v136, 1, v50
	v_mul_f32_e32 v50, 0xbfb8aa3b, v160
	v_mul_f32_e32 v52, v44, v50
	v_mul_f32_e32 v53, v45, v50
	v_mul_f32_e32 v44, v46, v50
	v_mul_f32_e32 v45, v47, v50
	v_exp_f32_e32 v52, v52
	v_exp_f32_e32 v53, v53
	v_exp_f32_e32 v44, v44
	v_exp_f32_e32 v45, v45
	v_cvt_pk_bf16_f32 v59, v48, v49
	v_add_f32_e32 v52, 1.0, v52
	v_add_f32_e32 v53, 1.0, v53
	v_mov_b64_e32 v[48:49], s[16:17]
	v_rcp_f32_e32 v52, v52
	v_rcp_f32_e32 v53, v53
	v_add_f32_e32 v44, 1.0, v44
	v_add_f32_e32 v45, 1.0, v45
	v_mad_i64_i32 v[48:49], s[2:3], v65, s37, v[48:49]
	v_rcp_f32_e32 v44, v44
	v_rcp_f32_e32 v45, v45
	v_mul_f32_e32 v46, v54, v52
	v_mul_f32_e32 v47, v54, v53
	v_mul_f32_e32 v40, v40, v46
	v_mul_f32_e32 v41, v41, v47
	v_mul_f32_e32 v46, v36, v50
	v_mul_f32_e32 v47, v37, v50
	v_mul_f32_e32 v44, v54, v44
	v_mul_f32_e32 v45, v54, v45
	v_exp_f32_e32 v46, v46
	v_exp_f32_e32 v47, v47
	v_mul_f32_e32 v42, v42, v44
	v_mul_f32_e32 v43, v43, v45
	v_mul_f32_e32 v44, v38, v50
	v_mul_f32_e32 v45, v39, v50
	v_lshl_add_u64 v[48:49], v[48:49], 0, v[136:137]
	v_exp_f32_e32 v44, v44
	v_exp_f32_e32 v45, v45
	v_lshl_add_u64 v[48:49], v[48:49], 0, v[112:113]
	global_store_dwordx4 v[48:49], v[56:59], off
	v_cvt_pk_bf16_f32 v40, v40, v41
	v_cvt_pk_bf16_f32 v41, v42, v43
	v_add_f32_e32 v42, 1.0, v46
	v_add_f32_e32 v43, 1.0, v47
	v_add_f32_e32 v36, 1.0, v44
	v_add_f32_e32 v37, 1.0, v45
	v_rcp_f32_e32 v42, v42
	v_rcp_f32_e32 v43, v43
	v_rcp_f32_e32 v36, v36
	v_rcp_f32_e32 v37, v37
	s_mov_b64 s[2:3], -1
	v_mul_f32_e32 v38, v54, v42
	v_mul_f32_e32 v39, v54, v43
	v_mul_f32_e32 v32, v32, v38
	v_mul_f32_e32 v33, v33, v39
	s_nop 0
	v_cvt_pk_bf16_f32 v42, v32, v33
	v_mul_f32_e32 v32, v54, v36
	v_mul_f32_e32 v33, v54, v37
	v_mul_f32_e32 v32, v34, v32
	v_mul_f32_e32 v33, v35, v33
	v_add_co_u32_e32 v36, vcc, s28, v48
	v_cvt_pk_bf16_f32 v43, v32, v33
	v_mul_f32_e32 v32, 0xbfb8aa3b, v159
	v_mul_f32_e32 v34, v28, v32
	v_mul_f32_e32 v35, v29, v32
	v_mul_f32_e32 v28, v30, v32
	v_mul_f32_e32 v29, v31, v32
	v_exp_f32_e32 v34, v34
	v_exp_f32_e32 v35, v35
	v_exp_f32_e32 v28, v28
	v_exp_f32_e32 v29, v29
	v_addc_co_u32_e32 v37, vcc, 0, v49, vcc
	v_add_f32_e32 v34, 1.0, v34
	v_add_f32_e32 v35, 1.0, v35
	v_add_f32_e32 v28, 1.0, v28
	v_add_f32_e32 v29, 1.0, v29
	v_rcp_f32_e32 v34, v34
	v_rcp_f32_e32 v35, v35
	v_rcp_f32_e32 v28, v28
	v_rcp_f32_e32 v29, v29
	global_store_dwordx4 v[36:37], v[40:43], off offset:2048
	v_mul_f32_e32 v36, v159, v159
	v_mul_f32_e32 v30, v36, v34
	v_mul_f32_e32 v31, v36, v35
	v_mul_f32_e32 v24, v24, v30
	v_mul_f32_e32 v25, v25, v31
	v_mul_f32_e32 v30, v20, v32
	v_mul_f32_e32 v31, v21, v32
	v_mul_f32_e32 v28, v36, v28
	v_mul_f32_e32 v29, v36, v29
	v_exp_f32_e32 v30, v30
	v_exp_f32_e32 v31, v31
	v_mul_f32_e32 v26, v26, v28
	v_mul_f32_e32 v27, v27, v29
	v_mul_f32_e32 v28, v22, v32
	v_mul_f32_e32 v29, v23, v32
	v_cvt_pk_bf16_f32 v24, v24, v25
	v_cvt_pk_bf16_f32 v25, v26, v27
	v_add_f32_e32 v26, 1.0, v30
	v_add_f32_e32 v27, 1.0, v31
	v_exp_f32_e32 v28, v28
	v_exp_f32_e32 v29, v29
	v_rcp_f32_e32 v26, v26
	v_rcp_f32_e32 v27, v27
	v_add_f32_e32 v20, 1.0, v28
	v_add_f32_e32 v21, 1.0, v29
	s_nop 0
	v_rcp_f32_e32 v20, v20
	v_rcp_f32_e32 v21, v21
	v_mul_f32_e32 v22, v36, v26
	v_mul_f32_e32 v23, v36, v27
	v_mul_f32_e32 v16, v16, v22
	v_mul_f32_e32 v17, v17, v23
	s_nop 0
	v_cvt_pk_bf16_f32 v26, v16, v17
	v_mul_f32_e32 v16, v36, v20
	v_mul_f32_e32 v17, v36, v21
	v_mul_f32_e32 v16, v18, v16
	v_mul_f32_e32 v17, v19, v17
	v_add_co_u32_e32 v20, vcc, s38, v48
	v_cvt_pk_bf16_f32 v27, v16, v17
	v_mul_f32_e32 v16, 0xbfb8aa3b, v147
	v_mul_f32_e32 v18, v12, v16
	v_mul_f32_e32 v19, v13, v16
	v_mul_f32_e32 v12, v14, v16
	v_mul_f32_e32 v13, v15, v16
	v_exp_f32_e32 v18, v18
	v_exp_f32_e32 v19, v19
	v_exp_f32_e32 v12, v12
	v_exp_f32_e32 v13, v13
	v_addc_co_u32_e32 v21, vcc, 0, v49, vcc
	v_add_f32_e32 v18, 1.0, v18
	v_add_f32_e32 v19, 1.0, v19
	v_add_f32_e32 v12, 1.0, v12
	v_add_f32_e32 v13, 1.0, v13
	v_rcp_f32_e32 v18, v18
	v_rcp_f32_e32 v19, v19
	v_rcp_f32_e32 v12, v12
	v_rcp_f32_e32 v13, v13
	global_store_dwordx4 v[20:21], v[24:27], off
	v_mul_f32_e32 v20, v147, v147
	v_mul_f32_e32 v14, v20, v18
	v_mul_f32_e32 v15, v20, v19
	v_mul_f32_e32 v8, v8, v14
	v_mul_f32_e32 v9, v9, v15
	v_mul_f32_e32 v14, v4, v16
	v_mul_f32_e32 v15, v5, v16
	v_mul_f32_e32 v12, v20, v12
	v_mul_f32_e32 v13, v20, v13
	v_exp_f32_e32 v14, v14
	v_exp_f32_e32 v15, v15
	v_mul_f32_e32 v10, v10, v12
	v_mul_f32_e32 v11, v11, v13
	v_mul_f32_e32 v12, v6, v16
	v_mul_f32_e32 v13, v7, v16
	v_cvt_pk_bf16_f32 v8, v8, v9
	v_cvt_pk_bf16_f32 v9, v10, v11
	v_add_f32_e32 v10, 1.0, v14
	v_add_f32_e32 v11, 1.0, v15
	v_exp_f32_e32 v12, v12
	v_exp_f32_e32 v13, v13
	v_rcp_f32_e32 v10, v10
	v_rcp_f32_e32 v11, v11
	v_add_f32_e32 v4, 1.0, v12
	v_add_f32_e32 v5, 1.0, v13
	s_nop 0
	v_rcp_f32_e32 v4, v4
	v_rcp_f32_e32 v5, v5
	v_mul_f32_e32 v6, v20, v10
	v_mul_f32_e32 v7, v20, v11
	v_mul_f32_e32 v0, v0, v6
	v_mul_f32_e32 v1, v1, v7
	s_nop 0
	v_cvt_pk_bf16_f32 v10, v0, v1
	v_mul_f32_e32 v0, v20, v4
	v_mul_f32_e32 v1, v20, v5
	v_mul_f32_e32 v0, v2, v0
	v_mul_f32_e32 v1, v3, v1
	s_nop 0
	v_cvt_pk_bf16_f32 v11, v0, v1
	v_add_co_u32_e32 v0, vcc, 0x43000, v48
	s_nop 1
	v_addc_co_u32_e32 v1, vcc, 0, v49, vcc
	s_andn2_b64 vcc, exec, s[4:5]
	global_store_dwordx4 v[0:1], v[8:11], off offset:2048
	s_cbranch_vccnz .LBB0_925
	s_andn2_b64 vcc, exec, s[0:1]
	s_cbranch_vccnz .LBB0_924
	s_barrier
	s_branch .LBB0_924
